# grid barrier: every block (leader too) invalidates L1 at arrival; out-proj epilogue stores write-through
# baseline (speedup 1.0000x reference)
.LBB0_60:
	s_or_saveexec_b64 s[10:11], s[10:11]
	v_max_u32_e32 v5, 1, v2
	s_xor_b64 exec, exec, s[10:11]
	s_cbranch_execz .LBB0_78
	s_mov_b64 s[12:13], exec
	buffer_wbl2 sc1
	buffer_inv sc1
	s_waitcnt vmcnt(0)
	v_mbcnt_lo_u32_b32 v2, s12, 0
	v_mbcnt_hi_u32_b32 v2, s13, v2
	v_cmp_eq_u32_e32 vcc, 0, v2
	s_and_saveexec_b64 s[14:15], vcc
	s_cbranch_execz .LBB0_63
	s_bcnt1_i32_b64 s3, s[12:13]
	v_mov_b32_e32 v3, 0x3000
	v_mov_b32_e32 v6, s3
	global_atomic_add v3, v3, v6, s[20:21] offset:1024 sc0

.LBB0_77:
	s_or_b64 exec, exec, s[6:7]
	v_mov_b32_e32 v2, 0x2000
	v_mov_b32_e32 v3, 1
	s_waitcnt vmcnt(0)
	global_atomic_add v2, v3, s[8:9] offset:1024
	s_waitcnt vmcnt(0)

.LBB0_124:
	s_andn2_saveexec_b64 s[8:9], s[8:9]
	s_cbranch_execz .LBB0_142
	s_mov_b64 s[10:11], exec
	buffer_wbl2 sc1
	buffer_inv sc1
	s_waitcnt vmcnt(0)
	v_mbcnt_lo_u32_b32 v3, s10, 0
	v_mbcnt_hi_u32_b32 v3, s11, v3
	v_cmp_eq_u32_e32 vcc, 0, v3
	s_and_saveexec_b64 s[12:13], vcc
	s_cbranch_execz .LBB0_127
	s_bcnt1_i32_b64 s3, s[10:11]
	v_mov_b32_e32 v5, 0x3000
	v_mov_b32_e32 v6, s3
	global_atomic_add v5, v5, v6, s[20:21] offset:1024 sc0

.LBB0_141:
	s_or_b64 exec, exec, s[10:11]
	v_mov_b32_e32 v3, 0x2000
	v_mov_b32_e32 v5, 1
	s_waitcnt vmcnt(0)
	global_atomic_add v3, v5, s[6:7] offset:1024
	s_waitcnt vmcnt(0)

.Lgm_ph5_loop:
	s_waitcnt lgkmcnt(1)
	v_mfma_f32_32x32x16_bf16 v[82:97], v[240:243], v[252:255], v[82:97]
	ds_read_b128 v[220:223], v210 offset:0
	v_mfma_f32_32x32x16_bf16 v[66:81], v[236:239], v[252:255], v[66:81]
	ds_read_b128 v[232:235], v214 offset:0
	v_mfma_f32_32x32x16_bf16 v[50:65], v[240:243], v[248:251], v[50:65]
	ds_read_b128 v[216:219], v210 offset:4096
	v_mfma_f32_32x32x16_bf16 v[34:49], v[236:239], v[248:251], v[34:49]
	ds_read_b128 v[228:231], v214 offset:4096
	s_waitcnt lgkmcnt(4)
	v_mfma_f32_32x32x16_bf16 v[18:33], v[240:243], v[244:247], v[18:33]
	ds_read_b128 v[224:227], v214 offset:8192
	v_mfma_f32_32x32x16_bf16 v[2:17], v[236:239], v[244:247], v[2:17]
	s_waitcnt lgkmcnt(1)
	v_mfma_f32_32x32x16_bf16 v[82:97], v[220:223], v[232:235], v[82:97]
	ds_read_b128 v[240:243], v209 offset:0
	v_mfma_f32_32x32x16_bf16 v[66:81], v[216:219], v[232:235], v[66:81]
	ds_read_b128 v[252:255], v213 offset:0
	v_mfma_f32_32x32x16_bf16 v[50:65], v[220:223], v[228:231], v[50:65]
	ds_read_b128 v[236:239], v209 offset:4096
	v_mfma_f32_32x32x16_bf16 v[34:49], v[216:219], v[228:231], v[34:49]
	ds_read_b128 v[248:251], v213 offset:4096
	s_waitcnt lgkmcnt(4)
	v_mfma_f32_32x32x16_bf16 v[18:33], v[220:223], v[224:227], v[18:33]
	ds_read_b128 v[244:247], v213 offset:8192
	v_mfma_f32_32x32x16_bf16 v[2:17], v[216:219], v[224:227], v[2:17]
	s_waitcnt lgkmcnt(1)
	v_mfma_f32_32x32x16_bf16 v[82:97], v[240:243], v[252:255], v[82:97]
	ds_read_b128 v[220:223], v208 offset:0
	s_add_u32 s83, s79, s78
	s_add_u32 s83, s83, 2
	s_and_b32 s83, s83, 15
	v_mfma_f32_32x32x16_bf16 v[66:81], v[236:239], v[252:255], v[66:81]
	ds_read_b128 v[232:235], v212 offset:0
	s_lshl_b32 s83, s83, 7
	s_add_u32 s70, s66, s83
	v_mfma_f32_32x32x16_bf16 v[50:65], v[240:243], v[248:251], v[50:65]
	ds_read_b128 v[216:219], v208 offset:4096
	s_addc_u32 s71, s67, 0
	s_add_u32 s72, s68, s83
	v_mfma_f32_32x32x16_bf16 v[34:49], v[236:239], v[248:251], v[34:49]
	ds_read_b128 v[228:231], v212 offset:4096
	s_addc_u32 s73, s69, 0
	s_add_u32 s81, s80, 0x0
	s_add_u32 s82, s80, 0xc000
	s_waitcnt lgkmcnt(4)
	v_mfma_f32_32x32x16_bf16 v[18:33], v[240:243], v[244:247], v[18:33]
	ds_read_b128 v[224:227], v212 offset:8192
	v_mfma_f32_32x32x16_bf16 v[2:17], v[236:239], v[244:247], v[2:17]
	s_waitcnt vmcnt(0) lgkmcnt(0)
	s_barrier
	v_mfma_f32_32x32x16_bf16 v[82:97], v[220:223], v[232:235], v[82:97]
	s_add_u32 m0, s81, 0x0
	ds_read_b128 v[240:243], v211 offset:16384
	global_load_lds_dwordx4 v207, s[70:71]
	s_add_u32 m0, s81, 0x1000
	s_nop 0
	global_load_lds_dwordx4 v206, s[70:71]
	v_mfma_f32_32x32x16_bf16 v[66:81], v[216:219], v[232:235], v[66:81]
	s_add_u32 m0, s81, 0x2000
	ds_read_b128 v[252:255], v215 offset:24576
	global_load_lds_dwordx4 v205, s[70:71]
	s_add_u32 m0, s81, 0x3000
	s_nop 0
	global_load_lds_dwordx4 v204, s[70:71]
	v_mfma_f32_32x32x16_bf16 v[50:65], v[220:223], v[228:231], v[50:65]
	s_add_u32 m0, s81, 0x4000
	ds_read_b128 v[236:239], v211 offset:20480
	global_load_lds_dwordx4 v203, s[70:71]
	s_add_u32 m0, s81, 0x5000
	s_nop 0
	global_load_lds_dwordx4 v202, s[70:71]
	v_mfma_f32_32x32x16_bf16 v[34:49], v[216:219], v[228:231], v[34:49]
	s_add_u32 m0, s82, 0x0
	ds_read_b128 v[248:251], v215 offset:28672
	global_load_lds_dwordx4 v207, s[72:73]
	s_add_u32 m0, s82, 0x1000
	s_nop 0
	global_load_lds_dwordx4 v206, s[72:73]
	v_mfma_f32_32x32x16_bf16 v[18:33], v[220:223], v[224:227], v[18:33]
	s_add_u32 m0, s82, 0x2000
	ds_read_b128 v[244:247], v215 offset:32768
	global_load_lds_dwordx4 v205, s[72:73]
	s_add_u32 m0, s82, 0x3000
	s_nop 0
	global_load_lds_dwordx4 v204, s[72:73]
	v_mfma_f32_32x32x16_bf16 v[2:17], v[216:219], v[224:227], v[2:17]
	s_waitcnt lgkmcnt(1)
	v_mfma_f32_32x32x16_bf16 v[82:97], v[240:243], v[252:255], v[82:97]
	ds_read_b128 v[220:223], v210 offset:16384
	v_mfma_f32_32x32x16_bf16 v[66:81], v[236:239], v[252:255], v[66:81]
	ds_read_b128 v[232:235], v214 offset:24576
	v_mfma_f32_32x32x16_bf16 v[50:65], v[240:243], v[248:251], v[50:65]
	ds_read_b128 v[216:219], v210 offset:20480
	v_mfma_f32_32x32x16_bf16 v[34:49], v[236:239], v[248:251], v[34:49]
	ds_read_b128 v[228:231], v214 offset:28672
	s_waitcnt lgkmcnt(4)
	v_mfma_f32_32x32x16_bf16 v[18:33], v[240:243], v[244:247], v[18:33]
	ds_read_b128 v[224:227], v214 offset:32768
	v_mfma_f32_32x32x16_bf16 v[2:17], v[236:239], v[244:247], v[2:17]
	s_waitcnt lgkmcnt(1)
	v_mfma_f32_32x32x16_bf16 v[82:97], v[220:223], v[232:235], v[82:97]
	ds_read_b128 v[240:243], v209 offset:16384
	v_mfma_f32_32x32x16_bf16 v[66:81], v[216:219], v[232:235], v[66:81]
	ds_read_b128 v[252:255], v213 offset:24576
	v_mfma_f32_32x32x16_bf16 v[50:65], v[220:223], v[228:231], v[50:65]
	ds_read_b128 v[236:239], v209 offset:20480
	v_mfma_f32_32x32x16_bf16 v[34:49], v[216:219], v[228:231], v[34:49]
	ds_read_b128 v[248:251], v213 offset:28672
	s_waitcnt lgkmcnt(4)
	v_mfma_f32_32x32x16_bf16 v[18:33], v[220:223], v[224:227], v[18:33]
	ds_read_b128 v[244:247], v213 offset:32768
	v_mfma_f32_32x32x16_bf16 v[2:17], v[216:219], v[224:227], v[2:17]
	s_waitcnt lgkmcnt(1)
	v_mfma_f32_32x32x16_bf16 v[82:97], v[240:243], v[252:255], v[82:97]
	ds_read_b128 v[220:223], v208 offset:16384
	s_add_u32 s83, s79, s78
	s_add_u32 s83, s83, 3
	s_and_b32 s83, s83, 15
	v_mfma_f32_32x32x16_bf16 v[66:81], v[236:239], v[252:255], v[66:81]
	ds_read_b128 v[232:235], v212 offset:24576
	s_lshl_b32 s83, s83, 7
	s_add_u32 s70, s66, s83
	v_mfma_f32_32x32x16_bf16 v[50:65], v[240:243], v[248:251], v[50:65]
	ds_read_b128 v[216:219], v208 offset:20480
	s_addc_u32 s71, s67, 0
	s_add_u32 s72, s68, s83
	v_mfma_f32_32x32x16_bf16 v[34:49], v[236:239], v[248:251], v[34:49]
	ds_read_b128 v[228:231], v212 offset:28672
	s_addc_u32 s73, s69, 0
	s_add_u32 s81, s80, 0x6000
	s_add_u32 s82, s80, 0x10000
	s_waitcnt lgkmcnt(4)
	v_mfma_f32_32x32x16_bf16 v[18:33], v[240:243], v[244:247], v[18:33]
	ds_read_b128 v[224:227], v212 offset:32768
	v_mfma_f32_32x32x16_bf16 v[2:17], v[236:239], v[244:247], v[2:17]
	s_waitcnt vmcnt(0) lgkmcnt(0)
	s_barrier
	v_mfma_f32_32x32x16_bf16 v[82:97], v[220:223], v[232:235], v[82:97]
	s_add_u32 m0, s81, 0x0
	ds_read_b128 v[240:243], v211 offset:0
	global_load_lds_dwordx4 v207, s[70:71]
	s_add_u32 m0, s81, 0x1000
	s_nop 0
	global_load_lds_dwordx4 v206, s[70:71]
	v_mfma_f32_32x32x16_bf16 v[66:81], v[216:219], v[232:235], v[66:81]
	s_add_u32 m0, s81, 0x2000
	ds_read_b128 v[252:255], v215 offset:0
	global_load_lds_dwordx4 v205, s[70:71]
	s_add_u32 m0, s81, 0x3000
	s_nop 0
	global_load_lds_dwordx4 v204, s[70:71]
	v_mfma_f32_32x32x16_bf16 v[50:65], v[220:223], v[228:231], v[50:65]
	s_add_u32 m0, s81, 0x4000
	ds_read_b128 v[236:239], v211 offset:4096
	global_load_lds_dwordx4 v203, s[70:71]
	s_add_u32 m0, s81, 0x5000
	s_nop 0
	global_load_lds_dwordx4 v202, s[70:71]
	v_mfma_f32_32x32x16_bf16 v[34:49], v[216:219], v[228:231], v[34:49]
	s_add_u32 m0, s82, 0x0
	ds_read_b128 v[248:251], v215 offset:4096
	global_load_lds_dwordx4 v207, s[72:73]
	s_add_u32 m0, s82, 0x1000
	s_nop 0
	global_load_lds_dwordx4 v206, s[72:73]
	v_mfma_f32_32x32x16_bf16 v[18:33], v[220:223], v[224:227], v[18:33]
	s_add_u32 m0, s82, 0x2000
	ds_read_b128 v[244:247], v215 offset:8192
	global_load_lds_dwordx4 v205, s[72:73]
	s_add_u32 m0, s82, 0x3000
	s_nop 0
	global_load_lds_dwordx4 v204, s[72:73]
	v_mfma_f32_32x32x16_bf16 v[2:17], v[216:219], v[224:227], v[2:17]
	s_add_u32 s78, s78, 2
	s_cmp_lt_u32 s78, 14
	s_cbranch_scc1 .Lgm_ph5_loop
	s_waitcnt lgkmcnt(1)
	v_mfma_f32_32x32x16_bf16 v[82:97], v[240:243], v[252:255], v[82:97]
	ds_read_b128 v[220:223], v210 offset:0
	v_mfma_f32_32x32x16_bf16 v[66:81], v[236:239], v[252:255], v[66:81]
	ds_read_b128 v[232:235], v214 offset:0
	v_mfma_f32_32x32x16_bf16 v[50:65], v[240:243], v[248:251], v[50:65]
	ds_read_b128 v[216:219], v210 offset:4096
	v_mfma_f32_32x32x16_bf16 v[34:49], v[236:239], v[248:251], v[34:49]
	ds_read_b128 v[228:231], v214 offset:4096
	s_waitcnt lgkmcnt(4)
	v_mfma_f32_32x32x16_bf16 v[18:33], v[240:243], v[244:247], v[18:33]
	ds_read_b128 v[224:227], v214 offset:8192
	v_mfma_f32_32x32x16_bf16 v[2:17], v[236:239], v[244:247], v[2:17]
	s_waitcnt lgkmcnt(1)
	v_mfma_f32_32x32x16_bf16 v[82:97], v[220:223], v[232:235], v[82:97]
	ds_read_b128 v[240:243], v209 offset:0
	v_mfma_f32_32x32x16_bf16 v[66:81], v[216:219], v[232:235], v[66:81]
	ds_read_b128 v[252:255], v213 offset:0
	v_mfma_f32_32x32x16_bf16 v[50:65], v[220:223], v[228:231], v[50:65]
	ds_read_b128 v[236:239], v209 offset:4096
	v_mfma_f32_32x32x16_bf16 v[34:49], v[216:219], v[228:231], v[34:49]
	ds_read_b128 v[248:251], v213 offset:4096
	s_waitcnt lgkmcnt(4)
	v_mfma_f32_32x32x16_bf16 v[18:33], v[220:223], v[224:227], v[18:33]
	ds_read_b128 v[244:247], v213 offset:8192
	v_mfma_f32_32x32x16_bf16 v[2:17], v[216:219], v[224:227], v[2:17]
	s_waitcnt lgkmcnt(1)
	v_mfma_f32_32x32x16_bf16 v[82:97], v[240:243], v[252:255], v[82:97]
	ds_read_b128 v[220:223], v208 offset:0
	v_mfma_f32_32x32x16_bf16 v[66:81], v[236:239], v[252:255], v[66:81]
	ds_read_b128 v[232:235], v212 offset:0
	v_mfma_f32_32x32x16_bf16 v[50:65], v[240:243], v[248:251], v[50:65]
	ds_read_b128 v[216:219], v208 offset:4096
	v_mfma_f32_32x32x16_bf16 v[34:49], v[236:239], v[248:251], v[34:49]
	ds_read_b128 v[228:231], v212 offset:4096
	s_waitcnt lgkmcnt(4)
	v_mfma_f32_32x32x16_bf16 v[18:33], v[240:243], v[244:247], v[18:33]
	ds_read_b128 v[224:227], v212 offset:8192
	v_mfma_f32_32x32x16_bf16 v[2:17], v[236:239], v[244:247], v[2:17]
	s_waitcnt vmcnt(0) lgkmcnt(0)
	s_barrier
	v_mfma_f32_32x32x16_bf16 v[82:97], v[220:223], v[232:235], v[82:97]
	ds_read_b128 v[240:243], v211 offset:16384
	v_mfma_f32_32x32x16_bf16 v[66:81], v[216:219], v[232:235], v[66:81]
	ds_read_b128 v[252:255], v215 offset:24576
	v_mfma_f32_32x32x16_bf16 v[50:65], v[220:223], v[228:231], v[50:65]
	ds_read_b128 v[236:239], v211 offset:20480
	v_mfma_f32_32x32x16_bf16 v[34:49], v[216:219], v[228:231], v[34:49]
	ds_read_b128 v[248:251], v215 offset:28672
	v_mfma_f32_32x32x16_bf16 v[18:33], v[220:223], v[224:227], v[18:33]
	ds_read_b128 v[244:247], v215 offset:32768
	v_mfma_f32_32x32x16_bf16 v[2:17], v[216:219], v[224:227], v[2:17]
	s_waitcnt lgkmcnt(1)
	v_mfma_f32_32x32x16_bf16 v[82:97], v[240:243], v[252:255], v[82:97]
	ds_read_b128 v[220:223], v210 offset:16384
	v_mfma_f32_32x32x16_bf16 v[66:81], v[236:239], v[252:255], v[66:81]
	ds_read_b128 v[232:235], v214 offset:24576
	v_mfma_f32_32x32x16_bf16 v[50:65], v[240:243], v[248:251], v[50:65]
	ds_read_b128 v[216:219], v210 offset:20480
	v_mfma_f32_32x32x16_bf16 v[34:49], v[236:239], v[248:251], v[34:49]
	ds_read_b128 v[228:231], v214 offset:28672
	s_waitcnt lgkmcnt(4)
	v_mfma_f32_32x32x16_bf16 v[18:33], v[240:243], v[244:247], v[18:33]
	ds_read_b128 v[224:227], v214 offset:32768
	v_mfma_f32_32x32x16_bf16 v[2:17], v[236:239], v[244:247], v[2:17]
	s_waitcnt lgkmcnt(1)
	v_mfma_f32_32x32x16_bf16 v[82:97], v[220:223], v[232:235], v[82:97]
	ds_read_b128 v[240:243], v209 offset:16384
	v_mfma_f32_32x32x16_bf16 v[66:81], v[216:219], v[232:235], v[66:81]
	ds_read_b128 v[252:255], v213 offset:24576
	v_mfma_f32_32x32x16_bf16 v[50:65], v[220:223], v[228:231], v[50:65]
	ds_read_b128 v[236:239], v209 offset:20480
	v_mfma_f32_32x32x16_bf16 v[34:49], v[216:219], v[228:231], v[34:49]
	ds_read_b128 v[248:251], v213 offset:28672
	s_waitcnt lgkmcnt(4)
	v_mfma_f32_32x32x16_bf16 v[18:33], v[220:223], v[224:227], v[18:33]
	ds_read_b128 v[244:247], v213 offset:32768
	v_mfma_f32_32x32x16_bf16 v[2:17], v[216:219], v[224:227], v[2:17]
	s_waitcnt lgkmcnt(1)
	v_mfma_f32_32x32x16_bf16 v[82:97], v[240:243], v[252:255], v[82:97]
	ds_read_b128 v[220:223], v208 offset:16384
	v_mfma_f32_32x32x16_bf16 v[66:81], v[236:239], v[252:255], v[66:81]
	ds_read_b128 v[232:235], v212 offset:24576
	v_mfma_f32_32x32x16_bf16 v[50:65], v[240:243], v[248:251], v[50:65]
	ds_read_b128 v[216:219], v208 offset:20480
	v_mfma_f32_32x32x16_bf16 v[34:49], v[236:239], v[248:251], v[34:49]
	ds_read_b128 v[228:231], v212 offset:28672
	s_waitcnt lgkmcnt(4)
	v_mfma_f32_32x32x16_bf16 v[18:33], v[240:243], v[244:247], v[18:33]
	ds_read_b128 v[224:227], v212 offset:32768
	v_mfma_f32_32x32x16_bf16 v[2:17], v[236:239], v[244:247], v[2:17]
	s_waitcnt vmcnt(0) lgkmcnt(0)
	s_barrier
	v_mfma_f32_32x32x16_bf16 v[82:97], v[220:223], v[232:235], v[82:97]
	v_mfma_f32_32x32x16_bf16 v[66:81], v[216:219], v[232:235], v[66:81]
	v_mfma_f32_32x32x16_bf16 v[50:65], v[220:223], v[228:231], v[50:65]
	v_mfma_f32_32x32x16_bf16 v[34:49], v[216:219], v[228:231], v[34:49]
	v_mfma_f32_32x32x16_bf16 v[18:33], v[220:223], v[224:227], v[18:33]
	v_mfma_f32_32x32x16_bf16 v[2:17], v[216:219], v[224:227], v[2:17]
	s_nop 7
	s_nop 7
	s_waitcnt lgkmcnt(0)
	s_nop 10
	ds_write_b128 v147, v[82:85]
	ds_write_b128 v147, v[86:89] offset:32
	ds_write_b128 v147, v[90:93] offset:64
	ds_write_b128 v147, v[94:97] offset:96
	ds_write_b128 v147, v[66:69] offset:128
	ds_write_b128 v147, v[70:73] offset:160
	ds_write_b128 v147, v[74:77] offset:192
	ds_write_b128 v147, v[78:81] offset:224
	s_waitcnt lgkmcnt(0)
	v_add_u32_e32 v104, s29, v111
	v_or_b32_e32 v244, s30, v120
	v_lshlrev_b32_e32 v242, 2, v244
	v_add_u32_e32 v242, s3, v242
	v_lshlrev_b32_e32 v243, 1, v244
	v_mov_b32_e32 v240, v104
	v_add_u32_e32 v241, 0xfffff000, v240
	v_lshrrev_b32_e32 v241, 11, v241
	v_mad_u32_u24 v241, v241, s26, s26
	v_lshlrev_b32_e32 v241, 2, v241
	v_or_b32_e32 v232, v240, v119
	v_or_b32_e32 v233, v240, v121
	v_or_b32_e32 v234, v240, v122
	v_or_b32_e32 v235, v240, v123
	v_or_b32_e32 v236, v240, v124
	v_or_b32_e32 v237, v240, v125
	v_or_b32_e32 v238, v240, v126
	v_or_b32_e32 v239, v240, v127
	v_cmp_lt_i32_e64 s[82:83], s27, v232
	v_cmp_lt_i32_e64 s[84:85], s27, v233
	v_cmp_lt_i32_e64 s[86:87], s27, v234
	v_cmp_lt_i32_e64 s[88:89], s27, v235
	v_cmp_lt_i32_e64 s[90:91], s27, v236
	v_cmp_lt_i32_e64 s[92:93], s27, v237
	v_cmp_lt_i32_e64 s[94:95], s27, v238
	v_cmp_lt_i32_e64 s[96:97], s27, v239
	s_waitcnt lgkmcnt(0)
	v_cndmask_b32_e64 v200, 0, v241, s[82:83]
	v_cndmask_b32_e64 v204, 0, v241, s[84:85]
	v_cndmask_b32_e64 v208, 0, v241, s[86:87]
	v_cndmask_b32_e64 v212, 0, v241, s[88:89]
	v_cndmask_b32_e64 v216, 0, v241, s[90:91]
	v_cndmask_b32_e64 v220, 0, v241, s[92:93]
	v_cndmask_b32_e64 v224, 0, v241, s[94:95]
	v_cndmask_b32_e64 v228, 0, v241, s[96:97]
	v_add_u32_e32 v200, v200, v242
	v_add_u32_e32 v204, v204, v242
	v_add_u32_e32 v208, v208, v242
	v_add_u32_e32 v212, v212, v242
	v_add_u32_e32 v216, v216, v242
	v_add_u32_e32 v220, v220, v242
	v_add_u32_e32 v224, v224, v242
	v_add_u32_e32 v228, v228, v242
	ds_read_b128 v[82:85], v149
	global_load_dwordx4 v[200:203], v200, s[4:5]
	ds_read_b128 v[86:89], v149 offset:1088
	global_load_dwordx4 v[204:207], v204, s[4:5]
	ds_read_b128 v[90:93], v149 offset:2176
	global_load_dwordx4 v[208:211], v208, s[4:5]
	ds_read_b128 v[94:97], v149 offset:3264
	global_load_dwordx4 v[212:215], v212, s[4:5]
	ds_read_b128 v[66:69], v149 offset:4352
	global_load_dwordx4 v[216:219], v216, s[4:5]
	ds_read_b128 v[70:73], v149 offset:5440
	global_load_dwordx4 v[220:223], v220, s[4:5]
	ds_read_b128 v[74:77], v149 offset:6528
	global_load_dwordx4 v[224:227], v224, s[4:5]
	ds_read_b128 v[78:81], v149 offset:7616
	global_load_dwordx4 v[228:231], v228, s[4:5]
	v_lshl_add_u32 v232, v232, 11, v243
	v_lshl_add_u32 v233, v233, 11, v243
	v_lshl_add_u32 v234, v234, 11, v243
	v_lshl_add_u32 v235, v235, 11, v243
	v_lshl_add_u32 v236, v236, 11, v243
	v_lshl_add_u32 v237, v237, 11, v243
	v_lshl_add_u32 v238, v238, 11, v243
	v_lshl_add_u32 v239, v239, 11, v243
	s_waitcnt vmcnt(7) lgkmcnt(7)
	v_mul_f32_e32 v82, v82, v200
	v_mul_f32_e32 v83, v83, v201
	v_mul_f32_e32 v84, v84, v202
	v_mul_f32_e32 v85, v85, v203
	v_cvt_pk_bf16_f32 v82, v82, v83
	v_cvt_pk_bf16_f32 v83, v84, v85
	global_store_dwordx2 v232, v[82:83], s[6:7] sc1
	s_waitcnt vmcnt(7) lgkmcnt(6)
	v_mul_f32_e32 v86, v86, v204
	v_mul_f32_e32 v87, v87, v205
	v_mul_f32_e32 v88, v88, v206
	v_mul_f32_e32 v89, v89, v207
	v_cvt_pk_bf16_f32 v86, v86, v87
	v_cvt_pk_bf16_f32 v87, v88, v89
	global_store_dwordx2 v233, v[86:87], s[6:7] sc1
	s_waitcnt vmcnt(7) lgkmcnt(5)
	v_mul_f32_e32 v90, v90, v208
	v_mul_f32_e32 v91, v91, v209
	v_mul_f32_e32 v92, v92, v210
	v_mul_f32_e32 v93, v93, v211
	v_cvt_pk_bf16_f32 v90, v90, v91
	v_cvt_pk_bf16_f32 v91, v92, v93
	global_store_dwordx2 v234, v[90:91], s[6:7] sc1
	s_waitcnt vmcnt(7) lgkmcnt(4)
	v_mul_f32_e32 v94, v94, v212
	v_mul_f32_e32 v95, v95, v213
	v_mul_f32_e32 v96, v96, v214
	v_mul_f32_e32 v97, v97, v215
	v_cvt_pk_bf16_f32 v94, v94, v95
	v_cvt_pk_bf16_f32 v95, v96, v97
	global_store_dwordx2 v235, v[94:95], s[6:7] sc1
	s_waitcnt vmcnt(7) lgkmcnt(3)
	v_mul_f32_e32 v66, v66, v216
	v_mul_f32_e32 v67, v67, v217
	v_mul_f32_e32 v68, v68, v218
	v_mul_f32_e32 v69, v69, v219
	v_cvt_pk_bf16_f32 v66, v66, v67
	v_cvt_pk_bf16_f32 v67, v68, v69
	global_store_dwordx2 v236, v[66:67], s[6:7] sc1
	s_waitcnt vmcnt(7) lgkmcnt(2)
	v_mul_f32_e32 v70, v70, v220
	v_mul_f32_e32 v71, v71, v221
	v_mul_f32_e32 v72, v72, v222
	v_mul_f32_e32 v73, v73, v223
	v_cvt_pk_bf16_f32 v70, v70, v71
	v_cvt_pk_bf16_f32 v71, v72, v73
	global_store_dwordx2 v237, v[70:71], s[6:7] sc1
	s_waitcnt vmcnt(7) lgkmcnt(1)
	v_mul_f32_e32 v74, v74, v224
	v_mul_f32_e32 v75, v75, v225
	v_mul_f32_e32 v76, v76, v226
	v_mul_f32_e32 v77, v77, v227
	v_cvt_pk_bf16_f32 v74, v74, v75
	v_cvt_pk_bf16_f32 v75, v76, v77
	global_store_dwordx2 v238, v[74:75], s[6:7] sc1
	s_waitcnt vmcnt(7) lgkmcnt(0)
	v_mul_f32_e32 v78, v78, v228
	v_mul_f32_e32 v79, v79, v229
	v_mul_f32_e32 v80, v80, v230
	v_mul_f32_e32 v81, v81, v231
	v_cvt_pk_bf16_f32 v78, v78, v79
	v_cvt_pk_bf16_f32 v79, v80, v81
	global_store_dwordx2 v239, v[78:79], s[6:7] sc1
	ds_write_b128 v147, v[50:53]
	ds_write_b128 v147, v[54:57] offset:32
	ds_write_b128 v147, v[58:61] offset:64
	ds_write_b128 v147, v[62:65] offset:96
	ds_write_b128 v147, v[34:37] offset:128
	ds_write_b128 v147, v[38:41] offset:160
	ds_write_b128 v147, v[42:45] offset:192
	ds_write_b128 v147, v[46:49] offset:224
	v_add_u32_e32 v240, 0x20, v104
	v_add_u32_e32 v241, 0xfffff000, v240
	v_lshrrev_b32_e32 v241, 11, v241
	v_mad_u32_u24 v241, v241, s26, s26
	v_lshlrev_b32_e32 v241, 2, v241
	v_or_b32_e32 v232, v240, v119
	v_or_b32_e32 v233, v240, v121
	v_or_b32_e32 v234, v240, v122
	v_or_b32_e32 v235, v240, v123
	v_or_b32_e32 v236, v240, v124
	v_or_b32_e32 v237, v240, v125
	v_or_b32_e32 v238, v240, v126
	v_or_b32_e32 v239, v240, v127
	v_cmp_lt_i32_e64 s[82:83], s27, v232
	v_cmp_lt_i32_e64 s[84:85], s27, v233
	v_cmp_lt_i32_e64 s[86:87], s27, v234
	v_cmp_lt_i32_e64 s[88:89], s27, v235
	v_cmp_lt_i32_e64 s[90:91], s27, v236
	v_cmp_lt_i32_e64 s[92:93], s27, v237
	v_cmp_lt_i32_e64 s[94:95], s27, v238
	v_cmp_lt_i32_e64 s[96:97], s27, v239
	s_waitcnt lgkmcnt(0)
	v_cndmask_b32_e64 v200, 0, v241, s[82:83]
	v_cndmask_b32_e64 v204, 0, v241, s[84:85]
	v_cndmask_b32_e64 v208, 0, v241, s[86:87]
	v_cndmask_b32_e64 v212, 0, v241, s[88:89]
	v_cndmask_b32_e64 v216, 0, v241, s[90:91]
	v_cndmask_b32_e64 v220, 0, v241, s[92:93]
	v_cndmask_b32_e64 v224, 0, v241, s[94:95]
	v_cndmask_b32_e64 v228, 0, v241, s[96:97]
	v_add_u32_e32 v200, v200, v242
	v_add_u32_e32 v204, v204, v242
	v_add_u32_e32 v208, v208, v242
	v_add_u32_e32 v212, v212, v242
	v_add_u32_e32 v216, v216, v242
	v_add_u32_e32 v220, v220, v242
	v_add_u32_e32 v224, v224, v242
	v_add_u32_e32 v228, v228, v242
	ds_read_b128 v[50:53], v149
	global_load_dwordx4 v[200:203], v200, s[4:5]
	ds_read_b128 v[54:57], v149 offset:1088
	global_load_dwordx4 v[204:207], v204, s[4:5]
	ds_read_b128 v[58:61], v149 offset:2176
	global_load_dwordx4 v[208:211], v208, s[4:5]
	ds_read_b128 v[62:65], v149 offset:3264
	global_load_dwordx4 v[212:215], v212, s[4:5]
	ds_read_b128 v[34:37], v149 offset:4352
	global_load_dwordx4 v[216:219], v216, s[4:5]
	ds_read_b128 v[38:41], v149 offset:5440
	global_load_dwordx4 v[220:223], v220, s[4:5]
	ds_read_b128 v[42:45], v149 offset:6528
	global_load_dwordx4 v[224:227], v224, s[4:5]
	ds_read_b128 v[46:49], v149 offset:7616
	global_load_dwordx4 v[228:231], v228, s[4:5]
	v_lshl_add_u32 v232, v232, 11, v243
	v_lshl_add_u32 v233, v233, 11, v243
	v_lshl_add_u32 v234, v234, 11, v243
	v_lshl_add_u32 v235, v235, 11, v243
	v_lshl_add_u32 v236, v236, 11, v243
	v_lshl_add_u32 v237, v237, 11, v243
	v_lshl_add_u32 v238, v238, 11, v243
	v_lshl_add_u32 v239, v239, 11, v243
	s_waitcnt vmcnt(7) lgkmcnt(7)
	v_mul_f32_e32 v50, v50, v200
	v_mul_f32_e32 v51, v51, v201
	v_mul_f32_e32 v52, v52, v202
	v_mul_f32_e32 v53, v53, v203
	v_cvt_pk_bf16_f32 v50, v50, v51
	v_cvt_pk_bf16_f32 v51, v52, v53
	global_store_dwordx2 v232, v[50:51], s[6:7] sc1
	s_waitcnt vmcnt(7) lgkmcnt(6)
	v_mul_f32_e32 v54, v54, v204
	v_mul_f32_e32 v55, v55, v205
	v_mul_f32_e32 v56, v56, v206
	v_mul_f32_e32 v57, v57, v207
	v_cvt_pk_bf16_f32 v54, v54, v55
	v_cvt_pk_bf16_f32 v55, v56, v57
	global_store_dwordx2 v233, v[54:55], s[6:7] sc1
	s_waitcnt vmcnt(7) lgkmcnt(5)
	v_mul_f32_e32 v58, v58, v208
	v_mul_f32_e32 v59, v59, v209
	v_mul_f32_e32 v60, v60, v210
	v_mul_f32_e32 v61, v61, v211
	v_cvt_pk_bf16_f32 v58, v58, v59
	v_cvt_pk_bf16_f32 v59, v60, v61
	global_store_dwordx2 v234, v[58:59], s[6:7] sc1
	s_waitcnt vmcnt(7) lgkmcnt(4)
	v_mul_f32_e32 v62, v62, v212
	v_mul_f32_e32 v63, v63, v213
	v_mul_f32_e32 v64, v64, v214
	v_mul_f32_e32 v65, v65, v215
	v_cvt_pk_bf16_f32 v62, v62, v63
	v_cvt_pk_bf16_f32 v63, v64, v65
	global_store_dwordx2 v235, v[62:63], s[6:7] sc1
	s_waitcnt vmcnt(7) lgkmcnt(3)
	v_mul_f32_e32 v34, v34, v216
	v_mul_f32_e32 v35, v35, v217
	v_mul_f32_e32 v36, v36, v218
	v_mul_f32_e32 v37, v37, v219
	v_cvt_pk_bf16_f32 v34, v34, v35
	v_cvt_pk_bf16_f32 v35, v36, v37
	global_store_dwordx2 v236, v[34:35], s[6:7] sc1
	s_waitcnt vmcnt(7) lgkmcnt(2)
	v_mul_f32_e32 v38, v38, v220
	v_mul_f32_e32 v39, v39, v221
	v_mul_f32_e32 v40, v40, v222
	v_mul_f32_e32 v41, v41, v223
	v_cvt_pk_bf16_f32 v38, v38, v39
	v_cvt_pk_bf16_f32 v39, v40, v41
	global_store_dwordx2 v237, v[38:39], s[6:7] sc1
	s_waitcnt vmcnt(7) lgkmcnt(1)
	v_mul_f32_e32 v42, v42, v224
	v_mul_f32_e32 v43, v43, v225
	v_mul_f32_e32 v44, v44, v226
	v_mul_f32_e32 v45, v45, v227
	v_cvt_pk_bf16_f32 v42, v42, v43
	v_cvt_pk_bf16_f32 v43, v44, v45
	global_store_dwordx2 v238, v[42:43], s[6:7] sc1
	s_waitcnt vmcnt(7) lgkmcnt(0)
	v_mul_f32_e32 v46, v46, v228
	v_mul_f32_e32 v47, v47, v229
	v_mul_f32_e32 v48, v48, v230
	v_mul_f32_e32 v49, v49, v231
	v_cvt_pk_bf16_f32 v46, v46, v47
	v_cvt_pk_bf16_f32 v47, v48, v49
	global_store_dwordx2 v239, v[46:47], s[6:7] sc1
	ds_write_b128 v147, v[18:21]
	ds_write_b128 v147, v[22:25] offset:32
	ds_write_b128 v147, v[26:29] offset:64
	ds_write_b128 v147, v[30:33] offset:96
	ds_write_b128 v147, v[2:5] offset:128
	ds_write_b128 v147, v[6:9] offset:160
	ds_write_b128 v147, v[10:13] offset:192
	ds_write_b128 v147, v[14:17] offset:224
	v_add_u32_e32 v240, 0x40, v104
	v_add_u32_e32 v241, 0xfffff000, v240
	v_lshrrev_b32_e32 v241, 11, v241
	v_mad_u32_u24 v241, v241, s26, s26
	v_lshlrev_b32_e32 v241, 2, v241
	v_or_b32_e32 v232, v240, v119
	v_or_b32_e32 v233, v240, v121
	v_or_b32_e32 v234, v240, v122
	v_or_b32_e32 v235, v240, v123
	v_or_b32_e32 v236, v240, v124
	v_or_b32_e32 v237, v240, v125
	v_or_b32_e32 v238, v240, v126
	v_or_b32_e32 v239, v240, v127
	v_cmp_lt_i32_e64 s[82:83], s27, v232
	v_cmp_lt_i32_e64 s[84:85], s27, v233
	v_cmp_lt_i32_e64 s[86:87], s27, v234
	v_cmp_lt_i32_e64 s[88:89], s27, v235
	v_cmp_lt_i32_e64 s[90:91], s27, v236
	v_cmp_lt_i32_e64 s[92:93], s27, v237
	v_cmp_lt_i32_e64 s[94:95], s27, v238
	v_cmp_lt_i32_e64 s[96:97], s27, v239
	s_waitcnt lgkmcnt(0)
	v_cndmask_b32_e64 v200, 0, v241, s[82:83]
	v_cndmask_b32_e64 v204, 0, v241, s[84:85]
	v_cndmask_b32_e64 v208, 0, v241, s[86:87]
	v_cndmask_b32_e64 v212, 0, v241, s[88:89]
	v_cndmask_b32_e64 v216, 0, v241, s[90:91]
	v_cndmask_b32_e64 v220, 0, v241, s[92:93]
	v_cndmask_b32_e64 v224, 0, v241, s[94:95]
	v_cndmask_b32_e64 v228, 0, v241, s[96:97]
	v_add_u32_e32 v200, v200, v242
	v_add_u32_e32 v204, v204, v242
	v_add_u32_e32 v208, v208, v242
	v_add_u32_e32 v212, v212, v242
	v_add_u32_e32 v216, v216, v242
	v_add_u32_e32 v220, v220, v242
	v_add_u32_e32 v224, v224, v242
	v_add_u32_e32 v228, v228, v242
	ds_read_b128 v[18:21], v149
	global_load_dwordx4 v[200:203], v200, s[4:5]
	ds_read_b128 v[22:25], v149 offset:1088
	global_load_dwordx4 v[204:207], v204, s[4:5]
	ds_read_b128 v[26:29], v149 offset:2176
	global_load_dwordx4 v[208:211], v208, s[4:5]
	ds_read_b128 v[30:33], v149 offset:3264
	global_load_dwordx4 v[212:215], v212, s[4:5]
	ds_read_b128 v[2:5], v149 offset:4352
	global_load_dwordx4 v[216:219], v216, s[4:5]
	ds_read_b128 v[6:9], v149 offset:5440
	global_load_dwordx4 v[220:223], v220, s[4:5]
	ds_read_b128 v[10:13], v149 offset:6528
	global_load_dwordx4 v[224:227], v224, s[4:5]
	ds_read_b128 v[14:17], v149 offset:7616
	global_load_dwordx4 v[228:231], v228, s[4:5]
	v_lshl_add_u32 v232, v232, 11, v243
	v_lshl_add_u32 v233, v233, 11, v243
	v_lshl_add_u32 v234, v234, 11, v243
	v_lshl_add_u32 v235, v235, 11, v243
	v_lshl_add_u32 v236, v236, 11, v243
	v_lshl_add_u32 v237, v237, 11, v243
	v_lshl_add_u32 v238, v238, 11, v243
	v_lshl_add_u32 v239, v239, 11, v243
	s_waitcnt vmcnt(7) lgkmcnt(7)
	v_mul_f32_e32 v18, v18, v200
	v_mul_f32_e32 v19, v19, v201
	v_mul_f32_e32 v20, v20, v202
	v_mul_f32_e32 v21, v21, v203
	v_cvt_pk_bf16_f32 v18, v18, v19
	v_cvt_pk_bf16_f32 v19, v20, v21
	global_store_dwordx2 v232, v[18:19], s[6:7] sc1
	s_waitcnt vmcnt(7) lgkmcnt(6)
	v_mul_f32_e32 v22, v22, v204
	v_mul_f32_e32 v23, v23, v205
	v_mul_f32_e32 v24, v24, v206
	v_mul_f32_e32 v25, v25, v207
	v_cvt_pk_bf16_f32 v22, v22, v23
	v_cvt_pk_bf16_f32 v23, v24, v25
	global_store_dwordx2 v233, v[22:23], s[6:7] sc1
	s_waitcnt vmcnt(7) lgkmcnt(5)
	v_mul_f32_e32 v26, v26, v208
	v_mul_f32_e32 v27, v27, v209
	v_mul_f32_e32 v28, v28, v210
	v_mul_f32_e32 v29, v29, v211
	v_cvt_pk_bf16_f32 v26, v26, v27
	v_cvt_pk_bf16_f32 v27, v28, v29
	global_store_dwordx2 v234, v[26:27], s[6:7] sc1
	s_waitcnt vmcnt(7) lgkmcnt(4)
	v_mul_f32_e32 v30, v30, v212
	v_mul_f32_e32 v31, v31, v213
	v_mul_f32_e32 v32, v32, v214
	v_mul_f32_e32 v33, v33, v215
	v_cvt_pk_bf16_f32 v30, v30, v31
	v_cvt_pk_bf16_f32 v31, v32, v33
	global_store_dwordx2 v235, v[30:31], s[6:7] sc1
	s_waitcnt vmcnt(7) lgkmcnt(3)
	v_mul_f32_e32 v2, v2, v216
	v_mul_f32_e32 v3, v3, v217
	v_mul_f32_e32 v4, v4, v218
	v_mul_f32_e32 v5, v5, v219
	v_cvt_pk_bf16_f32 v2, v2, v3
	v_cvt_pk_bf16_f32 v3, v4, v5
	global_store_dwordx2 v236, v[2:3], s[6:7] sc1
	s_waitcnt vmcnt(7) lgkmcnt(2)
	v_mul_f32_e32 v6, v6, v220
	v_mul_f32_e32 v7, v7, v221
	v_mul_f32_e32 v8, v8, v222
	v_mul_f32_e32 v9, v9, v223
	v_cvt_pk_bf16_f32 v6, v6, v7
	v_cvt_pk_bf16_f32 v7, v8, v9
	global_store_dwordx2 v237, v[6:7], s[6:7] sc1
	s_waitcnt vmcnt(7) lgkmcnt(1)
	v_mul_f32_e32 v10, v10, v224
	v_mul_f32_e32 v11, v11, v225
	v_mul_f32_e32 v12, v12, v226
	v_mul_f32_e32 v13, v13, v227
	v_cvt_pk_bf16_f32 v10, v10, v11
	v_cvt_pk_bf16_f32 v11, v12, v13
	global_store_dwordx2 v238, v[10:11], s[6:7] sc1
	s_waitcnt vmcnt(7) lgkmcnt(0)
	v_mul_f32_e32 v14, v14, v228
	v_mul_f32_e32 v15, v15, v229
	v_mul_f32_e32 v16, v16, v230
	v_mul_f32_e32 v17, v17, v231
	v_cvt_pk_bf16_f32 v14, v14, v15
	v_cvt_pk_bf16_f32 v15, v16, v17
	global_store_dwordx2 v239, v[14:15], s[6:7] sc1
	s_waitcnt lgkmcnt(0)
	s_load_dword s10, s[8:9], 0x0
	s_waitcnt lgkmcnt(0)
	s_add_i32 s28, s10, s28
	s_cmpk_lt_i32 s28, 0x200
	s_cbranch_scc1 .LBB0_489

.LBB0_523:
	s_andn2_saveexec_b64 s[8:9], s[8:9]
	s_cbranch_execz .LBB0_541
	s_mov_b64 s[10:11], exec
	buffer_wbl2 sc1
	buffer_inv sc1
	s_waitcnt vmcnt(0)
	v_mbcnt_lo_u32_b32 v5, s10, 0
	v_mbcnt_hi_u32_b32 v5, s11, v5
	v_cmp_eq_u32_e32 vcc, 0, v5
	s_and_saveexec_b64 s[12:13], vcc
	s_cbranch_execz .LBB0_526
	s_bcnt1_i32_b64 s3, s[10:11]
	v_mov_b32_e32 v6, 0x3000
	v_mov_b32_e32 v7, s3
	global_atomic_add v6, v6, v7, s[20:21] offset:1024 sc0

.LBB0_540:
	s_or_b64 exec, exec, s[10:11]
	v_mov_b32_e32 v5, 0x2000
	v_mov_b32_e32 v6, 1
	s_waitcnt vmcnt(0)
	global_atomic_add v5, v6, s[6:7] offset:1024
	s_waitcnt vmcnt(0)

.Lgm_ph11_loop:
	s_waitcnt lgkmcnt(1)
	v_mfma_f32_32x32x16_bf16 v[82:97], v[240:243], v[252:255], v[82:97]
	ds_read_b128 v[220:223], v210 offset:0
	v_mfma_f32_32x32x16_bf16 v[66:81], v[236:239], v[252:255], v[66:81]
	ds_read_b128 v[232:235], v214 offset:0
	v_mfma_f32_32x32x16_bf16 v[50:65], v[240:243], v[248:251], v[50:65]
	ds_read_b128 v[216:219], v210 offset:4096
	v_mfma_f32_32x32x16_bf16 v[34:49], v[236:239], v[248:251], v[34:49]
	ds_read_b128 v[228:231], v214 offset:4096
	s_waitcnt lgkmcnt(4)
	v_mfma_f32_32x32x16_bf16 v[18:33], v[240:243], v[244:247], v[18:33]
	ds_read_b128 v[224:227], v214 offset:8192
	v_mfma_f32_32x32x16_bf16 v[2:17], v[236:239], v[244:247], v[2:17]
	s_waitcnt lgkmcnt(1)
	v_mfma_f32_32x32x16_bf16 v[82:97], v[220:223], v[232:235], v[82:97]
	ds_read_b128 v[240:243], v209 offset:0
	v_mfma_f32_32x32x16_bf16 v[66:81], v[216:219], v[232:235], v[66:81]
	ds_read_b128 v[252:255], v213 offset:0
	v_mfma_f32_32x32x16_bf16 v[50:65], v[220:223], v[228:231], v[50:65]
	ds_read_b128 v[236:239], v209 offset:4096
	v_mfma_f32_32x32x16_bf16 v[34:49], v[216:219], v[228:231], v[34:49]
	ds_read_b128 v[248:251], v213 offset:4096
	s_waitcnt lgkmcnt(4)
	v_mfma_f32_32x32x16_bf16 v[18:33], v[220:223], v[224:227], v[18:33]
	ds_read_b128 v[244:247], v213 offset:8192
	v_mfma_f32_32x32x16_bf16 v[2:17], v[216:219], v[224:227], v[2:17]
	s_waitcnt lgkmcnt(1)
	v_mfma_f32_32x32x16_bf16 v[82:97], v[240:243], v[252:255], v[82:97]
	ds_read_b128 v[220:223], v208 offset:0
	s_add_u32 s83, s79, s78
	s_add_u32 s83, s83, 2
	s_and_b32 s83, s83, 15
	v_mfma_f32_32x32x16_bf16 v[66:81], v[236:239], v[252:255], v[66:81]
	ds_read_b128 v[232:235], v212 offset:0
	s_lshl_b32 s83, s83, 7
	s_add_u32 s70, s66, s83
	v_mfma_f32_32x32x16_bf16 v[50:65], v[240:243], v[248:251], v[50:65]
	ds_read_b128 v[216:219], v208 offset:4096
	s_addc_u32 s71, s67, 0
	s_add_u32 s72, s68, s83
	v_mfma_f32_32x32x16_bf16 v[34:49], v[236:239], v[248:251], v[34:49]
	ds_read_b128 v[228:231], v212 offset:4096
	s_addc_u32 s73, s69, 0
	s_add_u32 s81, s80, 0x0
	s_add_u32 s82, s80, 0xc000
	s_waitcnt lgkmcnt(4)
	v_mfma_f32_32x32x16_bf16 v[18:33], v[240:243], v[244:247], v[18:33]
	ds_read_b128 v[224:227], v212 offset:8192
	v_mfma_f32_32x32x16_bf16 v[2:17], v[236:239], v[244:247], v[2:17]
	s_waitcnt vmcnt(0) lgkmcnt(0)
	s_barrier
	v_mfma_f32_32x32x16_bf16 v[82:97], v[220:223], v[232:235], v[82:97]
	s_add_u32 m0, s81, 0x0
	ds_read_b128 v[240:243], v211 offset:16384
	global_load_lds_dwordx4 v207, s[70:71]
	s_add_u32 m0, s81, 0x1000
	s_nop 0
	global_load_lds_dwordx4 v206, s[70:71]
	v_mfma_f32_32x32x16_bf16 v[66:81], v[216:219], v[232:235], v[66:81]
	s_add_u32 m0, s81, 0x2000
	ds_read_b128 v[252:255], v215 offset:24576
	global_load_lds_dwordx4 v205, s[70:71]
	s_add_u32 m0, s81, 0x3000
	s_nop 0
	global_load_lds_dwordx4 v204, s[70:71]
	v_mfma_f32_32x32x16_bf16 v[50:65], v[220:223], v[228:231], v[50:65]
	s_add_u32 m0, s81, 0x4000
	ds_read_b128 v[236:239], v211 offset:20480
	global_load_lds_dwordx4 v203, s[70:71]
	s_add_u32 m0, s81, 0x5000
	s_nop 0
	global_load_lds_dwordx4 v202, s[70:71]
	v_mfma_f32_32x32x16_bf16 v[34:49], v[216:219], v[228:231], v[34:49]
	s_add_u32 m0, s82, 0x0
	ds_read_b128 v[248:251], v215 offset:28672
	global_load_lds_dwordx4 v207, s[72:73]
	s_add_u32 m0, s82, 0x1000
	s_nop 0
	global_load_lds_dwordx4 v206, s[72:73]
	v_mfma_f32_32x32x16_bf16 v[18:33], v[220:223], v[224:227], v[18:33]
	s_add_u32 m0, s82, 0x2000
	ds_read_b128 v[244:247], v215 offset:32768
	global_load_lds_dwordx4 v205, s[72:73]
	s_add_u32 m0, s82, 0x3000
	s_nop 0
	global_load_lds_dwordx4 v204, s[72:73]
	v_mfma_f32_32x32x16_bf16 v[2:17], v[216:219], v[224:227], v[2:17]
	s_waitcnt lgkmcnt(1)
	v_mfma_f32_32x32x16_bf16 v[82:97], v[240:243], v[252:255], v[82:97]
	ds_read_b128 v[220:223], v210 offset:16384
	v_mfma_f32_32x32x16_bf16 v[66:81], v[236:239], v[252:255], v[66:81]
	ds_read_b128 v[232:235], v214 offset:24576
	v_mfma_f32_32x32x16_bf16 v[50:65], v[240:243], v[248:251], v[50:65]
	ds_read_b128 v[216:219], v210 offset:20480
	v_mfma_f32_32x32x16_bf16 v[34:49], v[236:239], v[248:251], v[34:49]
	ds_read_b128 v[228:231], v214 offset:28672
	s_waitcnt lgkmcnt(4)
	v_mfma_f32_32x32x16_bf16 v[18:33], v[240:243], v[244:247], v[18:33]
	ds_read_b128 v[224:227], v214 offset:32768
	v_mfma_f32_32x32x16_bf16 v[2:17], v[236:239], v[244:247], v[2:17]
	s_waitcnt lgkmcnt(1)
	v_mfma_f32_32x32x16_bf16 v[82:97], v[220:223], v[232:235], v[82:97]
	ds_read_b128 v[240:243], v209 offset:16384
	v_mfma_f32_32x32x16_bf16 v[66:81], v[216:219], v[232:235], v[66:81]
	ds_read_b128 v[252:255], v213 offset:24576
	v_mfma_f32_32x32x16_bf16 v[50:65], v[220:223], v[228:231], v[50:65]
	ds_read_b128 v[236:239], v209 offset:20480
	v_mfma_f32_32x32x16_bf16 v[34:49], v[216:219], v[228:231], v[34:49]
	ds_read_b128 v[248:251], v213 offset:28672
	s_waitcnt lgkmcnt(4)
	v_mfma_f32_32x32x16_bf16 v[18:33], v[220:223], v[224:227], v[18:33]
	ds_read_b128 v[244:247], v213 offset:32768
	v_mfma_f32_32x32x16_bf16 v[2:17], v[216:219], v[224:227], v[2:17]
	s_waitcnt lgkmcnt(1)
	v_mfma_f32_32x32x16_bf16 v[82:97], v[240:243], v[252:255], v[82:97]
	ds_read_b128 v[220:223], v208 offset:16384
	s_add_u32 s83, s79, s78
	s_add_u32 s83, s83, 3
	s_and_b32 s83, s83, 15
	v_mfma_f32_32x32x16_bf16 v[66:81], v[236:239], v[252:255], v[66:81]
	ds_read_b128 v[232:235], v212 offset:24576
	s_lshl_b32 s83, s83, 7
	s_add_u32 s70, s66, s83
	v_mfma_f32_32x32x16_bf16 v[50:65], v[240:243], v[248:251], v[50:65]
	ds_read_b128 v[216:219], v208 offset:20480
	s_addc_u32 s71, s67, 0
	s_add_u32 s72, s68, s83
	v_mfma_f32_32x32x16_bf16 v[34:49], v[236:239], v[248:251], v[34:49]
	ds_read_b128 v[228:231], v212 offset:28672
	s_addc_u32 s73, s69, 0
	s_add_u32 s81, s80, 0x6000
	s_add_u32 s82, s80, 0x10000
	s_waitcnt lgkmcnt(4)
	v_mfma_f32_32x32x16_bf16 v[18:33], v[240:243], v[244:247], v[18:33]
	ds_read_b128 v[224:227], v212 offset:32768
	v_mfma_f32_32x32x16_bf16 v[2:17], v[236:239], v[244:247], v[2:17]
	s_waitcnt vmcnt(0) lgkmcnt(0)
	s_barrier
	v_mfma_f32_32x32x16_bf16 v[82:97], v[220:223], v[232:235], v[82:97]
	s_add_u32 m0, s81, 0x0
	ds_read_b128 v[240:243], v211 offset:0
	global_load_lds_dwordx4 v207, s[70:71]
	s_add_u32 m0, s81, 0x1000
	s_nop 0
	global_load_lds_dwordx4 v206, s[70:71]
	v_mfma_f32_32x32x16_bf16 v[66:81], v[216:219], v[232:235], v[66:81]
	s_add_u32 m0, s81, 0x2000
	ds_read_b128 v[252:255], v215 offset:0
	global_load_lds_dwordx4 v205, s[70:71]
	s_add_u32 m0, s81, 0x3000
	s_nop 0
	global_load_lds_dwordx4 v204, s[70:71]
	v_mfma_f32_32x32x16_bf16 v[50:65], v[220:223], v[228:231], v[50:65]
	s_add_u32 m0, s81, 0x4000
	ds_read_b128 v[236:239], v211 offset:4096
	global_load_lds_dwordx4 v203, s[70:71]
	s_add_u32 m0, s81, 0x5000
	s_nop 0
	global_load_lds_dwordx4 v202, s[70:71]
	v_mfma_f32_32x32x16_bf16 v[34:49], v[216:219], v[228:231], v[34:49]
	s_add_u32 m0, s82, 0x0
	ds_read_b128 v[248:251], v215 offset:4096
	global_load_lds_dwordx4 v207, s[72:73]
	s_add_u32 m0, s82, 0x1000
	s_nop 0
	global_load_lds_dwordx4 v206, s[72:73]
	v_mfma_f32_32x32x16_bf16 v[18:33], v[220:223], v[224:227], v[18:33]
	s_add_u32 m0, s82, 0x2000
	ds_read_b128 v[244:247], v215 offset:8192
	global_load_lds_dwordx4 v205, s[72:73]
	s_add_u32 m0, s82, 0x3000
	s_nop 0
	global_load_lds_dwordx4 v204, s[72:73]
	v_mfma_f32_32x32x16_bf16 v[2:17], v[216:219], v[224:227], v[2:17]
	s_add_u32 s78, s78, 2
	s_cmp_lt_u32 s78, 14
	s_cbranch_scc1 .Lgm_ph11_loop
	s_waitcnt lgkmcnt(1)
	v_mfma_f32_32x32x16_bf16 v[82:97], v[240:243], v[252:255], v[82:97]
	ds_read_b128 v[220:223], v210 offset:0
	v_mfma_f32_32x32x16_bf16 v[66:81], v[236:239], v[252:255], v[66:81]
	ds_read_b128 v[232:235], v214 offset:0
	v_mfma_f32_32x32x16_bf16 v[50:65], v[240:243], v[248:251], v[50:65]
	ds_read_b128 v[216:219], v210 offset:4096
	v_mfma_f32_32x32x16_bf16 v[34:49], v[236:239], v[248:251], v[34:49]
	ds_read_b128 v[228:231], v214 offset:4096
	s_waitcnt lgkmcnt(4)
	v_mfma_f32_32x32x16_bf16 v[18:33], v[240:243], v[244:247], v[18:33]
	ds_read_b128 v[224:227], v214 offset:8192
	v_mfma_f32_32x32x16_bf16 v[2:17], v[236:239], v[244:247], v[2:17]
	s_waitcnt lgkmcnt(1)
	v_mfma_f32_32x32x16_bf16 v[82:97], v[220:223], v[232:235], v[82:97]
	ds_read_b128 v[240:243], v209 offset:0
	v_mfma_f32_32x32x16_bf16 v[66:81], v[216:219], v[232:235], v[66:81]
	ds_read_b128 v[252:255], v213 offset:0
	v_mfma_f32_32x32x16_bf16 v[50:65], v[220:223], v[228:231], v[50:65]
	ds_read_b128 v[236:239], v209 offset:4096
	v_mfma_f32_32x32x16_bf16 v[34:49], v[216:219], v[228:231], v[34:49]
	ds_read_b128 v[248:251], v213 offset:4096
	s_waitcnt lgkmcnt(4)
	v_mfma_f32_32x32x16_bf16 v[18:33], v[220:223], v[224:227], v[18:33]
	ds_read_b128 v[244:247], v213 offset:8192
	v_mfma_f32_32x32x16_bf16 v[2:17], v[216:219], v[224:227], v[2:17]
	s_waitcnt lgkmcnt(1)
	v_mfma_f32_32x32x16_bf16 v[82:97], v[240:243], v[252:255], v[82:97]
	ds_read_b128 v[220:223], v208 offset:0
	v_mfma_f32_32x32x16_bf16 v[66:81], v[236:239], v[252:255], v[66:81]
	ds_read_b128 v[232:235], v212 offset:0
	v_mfma_f32_32x32x16_bf16 v[50:65], v[240:243], v[248:251], v[50:65]
	ds_read_b128 v[216:219], v208 offset:4096
	v_mfma_f32_32x32x16_bf16 v[34:49], v[236:239], v[248:251], v[34:49]
	ds_read_b128 v[228:231], v212 offset:4096
	s_waitcnt lgkmcnt(4)
	v_mfma_f32_32x32x16_bf16 v[18:33], v[240:243], v[244:247], v[18:33]
	ds_read_b128 v[224:227], v212 offset:8192
	v_mfma_f32_32x32x16_bf16 v[2:17], v[236:239], v[244:247], v[2:17]
	s_waitcnt vmcnt(0) lgkmcnt(0)
	s_barrier
	v_mfma_f32_32x32x16_bf16 v[82:97], v[220:223], v[232:235], v[82:97]
	ds_read_b128 v[240:243], v211 offset:16384
	v_mfma_f32_32x32x16_bf16 v[66:81], v[216:219], v[232:235], v[66:81]
	ds_read_b128 v[252:255], v215 offset:24576
	v_mfma_f32_32x32x16_bf16 v[50:65], v[220:223], v[228:231], v[50:65]
	ds_read_b128 v[236:239], v211 offset:20480
	v_mfma_f32_32x32x16_bf16 v[34:49], v[216:219], v[228:231], v[34:49]
	ds_read_b128 v[248:251], v215 offset:28672
	v_mfma_f32_32x32x16_bf16 v[18:33], v[220:223], v[224:227], v[18:33]
	ds_read_b128 v[244:247], v215 offset:32768
	v_mfma_f32_32x32x16_bf16 v[2:17], v[216:219], v[224:227], v[2:17]
	s_waitcnt lgkmcnt(1)
	v_mfma_f32_32x32x16_bf16 v[82:97], v[240:243], v[252:255], v[82:97]
	ds_read_b128 v[220:223], v210 offset:16384
	v_mfma_f32_32x32x16_bf16 v[66:81], v[236:239], v[252:255], v[66:81]
	ds_read_b128 v[232:235], v214 offset:24576
	v_mfma_f32_32x32x16_bf16 v[50:65], v[240:243], v[248:251], v[50:65]
	ds_read_b128 v[216:219], v210 offset:20480
	v_mfma_f32_32x32x16_bf16 v[34:49], v[236:239], v[248:251], v[34:49]
	ds_read_b128 v[228:231], v214 offset:28672
	s_waitcnt lgkmcnt(4)
	v_mfma_f32_32x32x16_bf16 v[18:33], v[240:243], v[244:247], v[18:33]
	ds_read_b128 v[224:227], v214 offset:32768
	v_mfma_f32_32x32x16_bf16 v[2:17], v[236:239], v[244:247], v[2:17]
	s_waitcnt lgkmcnt(1)
	v_mfma_f32_32x32x16_bf16 v[82:97], v[220:223], v[232:235], v[82:97]
	ds_read_b128 v[240:243], v209 offset:16384
	v_mfma_f32_32x32x16_bf16 v[66:81], v[216:219], v[232:235], v[66:81]
	ds_read_b128 v[252:255], v213 offset:24576
	v_mfma_f32_32x32x16_bf16 v[50:65], v[220:223], v[228:231], v[50:65]
	ds_read_b128 v[236:239], v209 offset:20480
	v_mfma_f32_32x32x16_bf16 v[34:49], v[216:219], v[228:231], v[34:49]
	ds_read_b128 v[248:251], v213 offset:28672
	s_waitcnt lgkmcnt(4)
	v_mfma_f32_32x32x16_bf16 v[18:33], v[220:223], v[224:227], v[18:33]
	ds_read_b128 v[244:247], v213 offset:32768
	v_mfma_f32_32x32x16_bf16 v[2:17], v[216:219], v[224:227], v[2:17]
	s_waitcnt lgkmcnt(1)
	v_mfma_f32_32x32x16_bf16 v[82:97], v[240:243], v[252:255], v[82:97]
	ds_read_b128 v[220:223], v208 offset:16384
	v_mfma_f32_32x32x16_bf16 v[66:81], v[236:239], v[252:255], v[66:81]
	ds_read_b128 v[232:235], v212 offset:24576
	v_mfma_f32_32x32x16_bf16 v[50:65], v[240:243], v[248:251], v[50:65]
	ds_read_b128 v[216:219], v208 offset:20480
	v_mfma_f32_32x32x16_bf16 v[34:49], v[236:239], v[248:251], v[34:49]
	ds_read_b128 v[228:231], v212 offset:28672
	s_waitcnt lgkmcnt(4)
	v_mfma_f32_32x32x16_bf16 v[18:33], v[240:243], v[244:247], v[18:33]
	ds_read_b128 v[224:227], v212 offset:32768
	v_mfma_f32_32x32x16_bf16 v[2:17], v[236:239], v[244:247], v[2:17]
	s_waitcnt vmcnt(0) lgkmcnt(0)
	s_barrier
	v_mfma_f32_32x32x16_bf16 v[82:97], v[220:223], v[232:235], v[82:97]
	v_mfma_f32_32x32x16_bf16 v[66:81], v[216:219], v[232:235], v[66:81]
	v_mfma_f32_32x32x16_bf16 v[50:65], v[220:223], v[228:231], v[50:65]
	v_mfma_f32_32x32x16_bf16 v[34:49], v[216:219], v[228:231], v[34:49]
	v_mfma_f32_32x32x16_bf16 v[18:33], v[220:223], v[224:227], v[18:33]
	v_mfma_f32_32x32x16_bf16 v[2:17], v[216:219], v[224:227], v[2:17]
	s_nop 7
	s_nop 7
	s_waitcnt lgkmcnt(0)
	s_nop 10
	ds_write_b128 v147, v[82:85]
	ds_write_b128 v147, v[86:89] offset:32
	ds_write_b128 v147, v[90:93] offset:64
	ds_write_b128 v147, v[94:97] offset:96
	ds_write_b128 v147, v[66:69] offset:128
	ds_write_b128 v147, v[70:73] offset:160
	ds_write_b128 v147, v[74:77] offset:192
	ds_write_b128 v147, v[78:81] offset:224
	s_waitcnt lgkmcnt(0)
	v_add_u32_e32 v104, s29, v111
	v_or_b32_e32 v244, s30, v120
	v_lshlrev_b32_e32 v242, 2, v244
	v_add_u32_e32 v242, s3, v242
	v_lshlrev_b32_e32 v243, 1, v244
	v_mov_b32_e32 v240, v104
	v_add_u32_e32 v241, 0xfffff000, v240
	v_lshrrev_b32_e32 v241, 11, v241
	v_mad_u32_u24 v241, v241, s26, s26
	v_lshlrev_b32_e32 v241, 2, v241
	v_or_b32_e32 v232, v240, v119
	v_or_b32_e32 v233, v240, v121
	v_or_b32_e32 v234, v240, v122
	v_or_b32_e32 v235, v240, v123
	v_or_b32_e32 v236, v240, v124
	v_or_b32_e32 v237, v240, v125
	v_or_b32_e32 v238, v240, v126
	v_or_b32_e32 v239, v240, v127
	v_cmp_lt_i32_e64 s[82:83], s27, v232
	v_cmp_lt_i32_e64 s[84:85], s27, v233
	v_cmp_lt_i32_e64 s[86:87], s27, v234
	v_cmp_lt_i32_e64 s[88:89], s27, v235
	v_cmp_lt_i32_e64 s[90:91], s27, v236
	v_cmp_lt_i32_e64 s[92:93], s27, v237
	v_cmp_lt_i32_e64 s[94:95], s27, v238
	v_cmp_lt_i32_e64 s[96:97], s27, v239
	s_waitcnt lgkmcnt(0)
	v_cndmask_b32_e64 v200, 0, v241, s[82:83]
	v_cndmask_b32_e64 v204, 0, v241, s[84:85]
	v_cndmask_b32_e64 v208, 0, v241, s[86:87]
	v_cndmask_b32_e64 v212, 0, v241, s[88:89]
	v_cndmask_b32_e64 v216, 0, v241, s[90:91]
	v_cndmask_b32_e64 v220, 0, v241, s[92:93]
	v_cndmask_b32_e64 v224, 0, v241, s[94:95]
	v_cndmask_b32_e64 v228, 0, v241, s[96:97]
	v_add_u32_e32 v200, v200, v242
	v_add_u32_e32 v204, v204, v242
	v_add_u32_e32 v208, v208, v242
	v_add_u32_e32 v212, v212, v242
	v_add_u32_e32 v216, v216, v242
	v_add_u32_e32 v220, v220, v242
	v_add_u32_e32 v224, v224, v242
	v_add_u32_e32 v228, v228, v242
	ds_read_b128 v[82:85], v149
	global_load_dwordx4 v[200:203], v200, s[6:7]
	ds_read_b128 v[86:89], v149 offset:1088
	global_load_dwordx4 v[204:207], v204, s[6:7]
	ds_read_b128 v[90:93], v149 offset:2176
	global_load_dwordx4 v[208:211], v208, s[6:7]
	ds_read_b128 v[94:97], v149 offset:3264
	global_load_dwordx4 v[212:215], v212, s[6:7]
	ds_read_b128 v[66:69], v149 offset:4352
	global_load_dwordx4 v[216:219], v216, s[6:7]
	ds_read_b128 v[70:73], v149 offset:5440
	global_load_dwordx4 v[220:223], v220, s[6:7]
	ds_read_b128 v[74:77], v149 offset:6528
	global_load_dwordx4 v[224:227], v224, s[6:7]
	ds_read_b128 v[78:81], v149 offset:7616
	global_load_dwordx4 v[228:231], v228, s[6:7]
	v_lshl_add_u32 v232, v232, 11, v243
	v_lshl_add_u32 v233, v233, 11, v243
	v_lshl_add_u32 v234, v234, 11, v243
	v_lshl_add_u32 v235, v235, 11, v243
	v_lshl_add_u32 v236, v236, 11, v243
	v_lshl_add_u32 v237, v237, 11, v243
	v_lshl_add_u32 v238, v238, 11, v243
	v_lshl_add_u32 v239, v239, 11, v243
	s_waitcnt vmcnt(7) lgkmcnt(7)
	v_mul_f32_e32 v82, v82, v200
	v_mul_f32_e32 v83, v83, v201
	v_mul_f32_e32 v84, v84, v202
	v_mul_f32_e32 v85, v85, v203
	v_cvt_pk_bf16_f32 v82, v82, v83
	v_cvt_pk_bf16_f32 v83, v84, v85
	global_store_dwordx2 v232, v[82:83], s[4:5] sc1
	s_waitcnt vmcnt(7) lgkmcnt(6)
	v_mul_f32_e32 v86, v86, v204
	v_mul_f32_e32 v87, v87, v205
	v_mul_f32_e32 v88, v88, v206
	v_mul_f32_e32 v89, v89, v207
	v_cvt_pk_bf16_f32 v86, v86, v87
	v_cvt_pk_bf16_f32 v87, v88, v89
	global_store_dwordx2 v233, v[86:87], s[4:5] sc1
	s_waitcnt vmcnt(7) lgkmcnt(5)
	v_mul_f32_e32 v90, v90, v208
	v_mul_f32_e32 v91, v91, v209
	v_mul_f32_e32 v92, v92, v210
	v_mul_f32_e32 v93, v93, v211
	v_cvt_pk_bf16_f32 v90, v90, v91
	v_cvt_pk_bf16_f32 v91, v92, v93
	global_store_dwordx2 v234, v[90:91], s[4:5] sc1
	s_waitcnt vmcnt(7) lgkmcnt(4)
	v_mul_f32_e32 v94, v94, v212
	v_mul_f32_e32 v95, v95, v213
	v_mul_f32_e32 v96, v96, v214
	v_mul_f32_e32 v97, v97, v215
	v_cvt_pk_bf16_f32 v94, v94, v95
	v_cvt_pk_bf16_f32 v95, v96, v97
	global_store_dwordx2 v235, v[94:95], s[4:5] sc1
	s_waitcnt vmcnt(7) lgkmcnt(3)
	v_mul_f32_e32 v66, v66, v216
	v_mul_f32_e32 v67, v67, v217
	v_mul_f32_e32 v68, v68, v218
	v_mul_f32_e32 v69, v69, v219
	v_cvt_pk_bf16_f32 v66, v66, v67
	v_cvt_pk_bf16_f32 v67, v68, v69
	global_store_dwordx2 v236, v[66:67], s[4:5] sc1
	s_waitcnt vmcnt(7) lgkmcnt(2)
	v_mul_f32_e32 v70, v70, v220
	v_mul_f32_e32 v71, v71, v221
	v_mul_f32_e32 v72, v72, v222
	v_mul_f32_e32 v73, v73, v223
	v_cvt_pk_bf16_f32 v70, v70, v71
	v_cvt_pk_bf16_f32 v71, v72, v73
	global_store_dwordx2 v237, v[70:71], s[4:5] sc1
	s_waitcnt vmcnt(7) lgkmcnt(1)
	v_mul_f32_e32 v74, v74, v224
	v_mul_f32_e32 v75, v75, v225
	v_mul_f32_e32 v76, v76, v226
	v_mul_f32_e32 v77, v77, v227
	v_cvt_pk_bf16_f32 v74, v74, v75
	v_cvt_pk_bf16_f32 v75, v76, v77
	global_store_dwordx2 v238, v[74:75], s[4:5] sc1
	s_waitcnt vmcnt(7) lgkmcnt(0)
	v_mul_f32_e32 v78, v78, v228
	v_mul_f32_e32 v79, v79, v229
	v_mul_f32_e32 v80, v80, v230
	v_mul_f32_e32 v81, v81, v231
	v_cvt_pk_bf16_f32 v78, v78, v79
	v_cvt_pk_bf16_f32 v79, v80, v81
	global_store_dwordx2 v239, v[78:79], s[4:5] sc1
	ds_write_b128 v147, v[50:53]
	ds_write_b128 v147, v[54:57] offset:32
	ds_write_b128 v147, v[58:61] offset:64
	ds_write_b128 v147, v[62:65] offset:96
	ds_write_b128 v147, v[34:37] offset:128
	ds_write_b128 v147, v[38:41] offset:160
	ds_write_b128 v147, v[42:45] offset:192
	ds_write_b128 v147, v[46:49] offset:224
	v_add_u32_e32 v240, 0x20, v104
	v_add_u32_e32 v241, 0xfffff000, v240
	v_lshrrev_b32_e32 v241, 11, v241
	v_mad_u32_u24 v241, v241, s26, s26
	v_lshlrev_b32_e32 v241, 2, v241
	v_or_b32_e32 v232, v240, v119
	v_or_b32_e32 v233, v240, v121
	v_or_b32_e32 v234, v240, v122
	v_or_b32_e32 v235, v240, v123
	v_or_b32_e32 v236, v240, v124
	v_or_b32_e32 v237, v240, v125
	v_or_b32_e32 v238, v240, v126
	v_or_b32_e32 v239, v240, v127
	v_cmp_lt_i32_e64 s[82:83], s27, v232
	v_cmp_lt_i32_e64 s[84:85], s27, v233
	v_cmp_lt_i32_e64 s[86:87], s27, v234
	v_cmp_lt_i32_e64 s[88:89], s27, v235
	v_cmp_lt_i32_e64 s[90:91], s27, v236
	v_cmp_lt_i32_e64 s[92:93], s27, v237
	v_cmp_lt_i32_e64 s[94:95], s27, v238
	v_cmp_lt_i32_e64 s[96:97], s27, v239
	s_waitcnt lgkmcnt(0)
	v_cndmask_b32_e64 v200, 0, v241, s[82:83]
	v_cndmask_b32_e64 v204, 0, v241, s[84:85]
	v_cndmask_b32_e64 v208, 0, v241, s[86:87]
	v_cndmask_b32_e64 v212, 0, v241, s[88:89]
	v_cndmask_b32_e64 v216, 0, v241, s[90:91]
	v_cndmask_b32_e64 v220, 0, v241, s[92:93]
	v_cndmask_b32_e64 v224, 0, v241, s[94:95]
	v_cndmask_b32_e64 v228, 0, v241, s[96:97]
	v_add_u32_e32 v200, v200, v242
	v_add_u32_e32 v204, v204, v242
	v_add_u32_e32 v208, v208, v242
	v_add_u32_e32 v212, v212, v242
	v_add_u32_e32 v216, v216, v242
	v_add_u32_e32 v220, v220, v242
	v_add_u32_e32 v224, v224, v242
	v_add_u32_e32 v228, v228, v242
	ds_read_b128 v[50:53], v149
	global_load_dwordx4 v[200:203], v200, s[6:7]
	ds_read_b128 v[54:57], v149 offset:1088
	global_load_dwordx4 v[204:207], v204, s[6:7]
	ds_read_b128 v[58:61], v149 offset:2176
	global_load_dwordx4 v[208:211], v208, s[6:7]
	ds_read_b128 v[62:65], v149 offset:3264
	global_load_dwordx4 v[212:215], v212, s[6:7]
	ds_read_b128 v[34:37], v149 offset:4352
	global_load_dwordx4 v[216:219], v216, s[6:7]
	ds_read_b128 v[38:41], v149 offset:5440
	global_load_dwordx4 v[220:223], v220, s[6:7]
	ds_read_b128 v[42:45], v149 offset:6528
	global_load_dwordx4 v[224:227], v224, s[6:7]
	ds_read_b128 v[46:49], v149 offset:7616
	global_load_dwordx4 v[228:231], v228, s[6:7]
	v_lshl_add_u32 v232, v232, 11, v243
	v_lshl_add_u32 v233, v233, 11, v243
	v_lshl_add_u32 v234, v234, 11, v243
	v_lshl_add_u32 v235, v235, 11, v243
	v_lshl_add_u32 v236, v236, 11, v243
	v_lshl_add_u32 v237, v237, 11, v243
	v_lshl_add_u32 v238, v238, 11, v243
	v_lshl_add_u32 v239, v239, 11, v243
	s_waitcnt vmcnt(7) lgkmcnt(7)
	v_mul_f32_e32 v50, v50, v200
	v_mul_f32_e32 v51, v51, v201
	v_mul_f32_e32 v52, v52, v202
	v_mul_f32_e32 v53, v53, v203
	v_cvt_pk_bf16_f32 v50, v50, v51
	v_cvt_pk_bf16_f32 v51, v52, v53
	global_store_dwordx2 v232, v[50:51], s[4:5] sc1
	s_waitcnt vmcnt(7) lgkmcnt(6)
	v_mul_f32_e32 v54, v54, v204
	v_mul_f32_e32 v55, v55, v205
	v_mul_f32_e32 v56, v56, v206
	v_mul_f32_e32 v57, v57, v207
	v_cvt_pk_bf16_f32 v54, v54, v55
	v_cvt_pk_bf16_f32 v55, v56, v57
	global_store_dwordx2 v233, v[54:55], s[4:5] sc1
	s_waitcnt vmcnt(7) lgkmcnt(5)
	v_mul_f32_e32 v58, v58, v208
	v_mul_f32_e32 v59, v59, v209
	v_mul_f32_e32 v60, v60, v210
	v_mul_f32_e32 v61, v61, v211
	v_cvt_pk_bf16_f32 v58, v58, v59
	v_cvt_pk_bf16_f32 v59, v60, v61
	global_store_dwordx2 v234, v[58:59], s[4:5] sc1
	s_waitcnt vmcnt(7) lgkmcnt(4)
	v_mul_f32_e32 v62, v62, v212
	v_mul_f32_e32 v63, v63, v213
	v_mul_f32_e32 v64, v64, v214
	v_mul_f32_e32 v65, v65, v215
	v_cvt_pk_bf16_f32 v62, v62, v63
	v_cvt_pk_bf16_f32 v63, v64, v65
	global_store_dwordx2 v235, v[62:63], s[4:5] sc1
	s_waitcnt vmcnt(7) lgkmcnt(3)
	v_mul_f32_e32 v34, v34, v216
	v_mul_f32_e32 v35, v35, v217
	v_mul_f32_e32 v36, v36, v218
	v_mul_f32_e32 v37, v37, v219
	v_cvt_pk_bf16_f32 v34, v34, v35
	v_cvt_pk_bf16_f32 v35, v36, v37
	global_store_dwordx2 v236, v[34:35], s[4:5] sc1
	s_waitcnt vmcnt(7) lgkmcnt(2)
	v_mul_f32_e32 v38, v38, v220
	v_mul_f32_e32 v39, v39, v221
	v_mul_f32_e32 v40, v40, v222
	v_mul_f32_e32 v41, v41, v223
	v_cvt_pk_bf16_f32 v38, v38, v39
	v_cvt_pk_bf16_f32 v39, v40, v41
	global_store_dwordx2 v237, v[38:39], s[4:5] sc1
	s_waitcnt vmcnt(7) lgkmcnt(1)
	v_mul_f32_e32 v42, v42, v224
	v_mul_f32_e32 v43, v43, v225
	v_mul_f32_e32 v44, v44, v226
	v_mul_f32_e32 v45, v45, v227
	v_cvt_pk_bf16_f32 v42, v42, v43
	v_cvt_pk_bf16_f32 v43, v44, v45
	global_store_dwordx2 v238, v[42:43], s[4:5] sc1
	s_waitcnt vmcnt(7) lgkmcnt(0)
	v_mul_f32_e32 v46, v46, v228
	v_mul_f32_e32 v47, v47, v229
	v_mul_f32_e32 v48, v48, v230
	v_mul_f32_e32 v49, v49, v231
	v_cvt_pk_bf16_f32 v46, v46, v47
	v_cvt_pk_bf16_f32 v47, v48, v49
	global_store_dwordx2 v239, v[46:47], s[4:5] sc1
	ds_write_b128 v147, v[18:21]
	ds_write_b128 v147, v[22:25] offset:32
	ds_write_b128 v147, v[26:29] offset:64
	ds_write_b128 v147, v[30:33] offset:96
	ds_write_b128 v147, v[2:5] offset:128
	ds_write_b128 v147, v[6:9] offset:160
	ds_write_b128 v147, v[10:13] offset:192
	ds_write_b128 v147, v[14:17] offset:224
	v_add_u32_e32 v240, 0x40, v104
	v_add_u32_e32 v241, 0xfffff000, v240
	v_lshrrev_b32_e32 v241, 11, v241
	v_mad_u32_u24 v241, v241, s26, s26
	v_lshlrev_b32_e32 v241, 2, v241
	v_or_b32_e32 v232, v240, v119
	v_or_b32_e32 v233, v240, v121
	v_or_b32_e32 v234, v240, v122
	v_or_b32_e32 v235, v240, v123
	v_or_b32_e32 v236, v240, v124
	v_or_b32_e32 v237, v240, v125
	v_or_b32_e32 v238, v240, v126
	v_or_b32_e32 v239, v240, v127
	v_cmp_lt_i32_e64 s[82:83], s27, v232
	v_cmp_lt_i32_e64 s[84:85], s27, v233
	v_cmp_lt_i32_e64 s[86:87], s27, v234
	v_cmp_lt_i32_e64 s[88:89], s27, v235
	v_cmp_lt_i32_e64 s[90:91], s27, v236
	v_cmp_lt_i32_e64 s[92:93], s27, v237
	v_cmp_lt_i32_e64 s[94:95], s27, v238
	v_cmp_lt_i32_e64 s[96:97], s27, v239
	s_waitcnt lgkmcnt(0)
	v_cndmask_b32_e64 v200, 0, v241, s[82:83]
	v_cndmask_b32_e64 v204, 0, v241, s[84:85]
	v_cndmask_b32_e64 v208, 0, v241, s[86:87]
	v_cndmask_b32_e64 v212, 0, v241, s[88:89]
	v_cndmask_b32_e64 v216, 0, v241, s[90:91]
	v_cndmask_b32_e64 v220, 0, v241, s[92:93]
	v_cndmask_b32_e64 v224, 0, v241, s[94:95]
	v_cndmask_b32_e64 v228, 0, v241, s[96:97]
	v_add_u32_e32 v200, v200, v242
	v_add_u32_e32 v204, v204, v242
	v_add_u32_e32 v208, v208, v242
	v_add_u32_e32 v212, v212, v242
	v_add_u32_e32 v216, v216, v242
	v_add_u32_e32 v220, v220, v242
	v_add_u32_e32 v224, v224, v242
	v_add_u32_e32 v228, v228, v242
	ds_read_b128 v[18:21], v149
	global_load_dwordx4 v[200:203], v200, s[6:7]
	ds_read_b128 v[22:25], v149 offset:1088
	global_load_dwordx4 v[204:207], v204, s[6:7]
	ds_read_b128 v[26:29], v149 offset:2176
	global_load_dwordx4 v[208:211], v208, s[6:7]
	ds_read_b128 v[30:33], v149 offset:3264
	global_load_dwordx4 v[212:215], v212, s[6:7]
	ds_read_b128 v[2:5], v149 offset:4352
	global_load_dwordx4 v[216:219], v216, s[6:7]
	ds_read_b128 v[6:9], v149 offset:5440
	global_load_dwordx4 v[220:223], v220, s[6:7]
	ds_read_b128 v[10:13], v149 offset:6528
	global_load_dwordx4 v[224:227], v224, s[6:7]
	ds_read_b128 v[14:17], v149 offset:7616
	global_load_dwordx4 v[228:231], v228, s[6:7]
	v_lshl_add_u32 v232, v232, 11, v243
	v_lshl_add_u32 v233, v233, 11, v243
	v_lshl_add_u32 v234, v234, 11, v243
	v_lshl_add_u32 v235, v235, 11, v243
	v_lshl_add_u32 v236, v236, 11, v243
	v_lshl_add_u32 v237, v237, 11, v243
	v_lshl_add_u32 v238, v238, 11, v243
	v_lshl_add_u32 v239, v239, 11, v243
	s_waitcnt vmcnt(7) lgkmcnt(7)
	v_mul_f32_e32 v18, v18, v200
	v_mul_f32_e32 v19, v19, v201
	v_mul_f32_e32 v20, v20, v202
	v_mul_f32_e32 v21, v21, v203
	v_cvt_pk_bf16_f32 v18, v18, v19
	v_cvt_pk_bf16_f32 v19, v20, v21
	global_store_dwordx2 v232, v[18:19], s[4:5] sc1
	s_waitcnt vmcnt(7) lgkmcnt(6)
	v_mul_f32_e32 v22, v22, v204
	v_mul_f32_e32 v23, v23, v205
	v_mul_f32_e32 v24, v24, v206
	v_mul_f32_e32 v25, v25, v207
	v_cvt_pk_bf16_f32 v22, v22, v23
	v_cvt_pk_bf16_f32 v23, v24, v25
	global_store_dwordx2 v233, v[22:23], s[4:5] sc1
	s_waitcnt vmcnt(7) lgkmcnt(5)
	v_mul_f32_e32 v26, v26, v208
	v_mul_f32_e32 v27, v27, v209
	v_mul_f32_e32 v28, v28, v210
	v_mul_f32_e32 v29, v29, v211
	v_cvt_pk_bf16_f32 v26, v26, v27
	v_cvt_pk_bf16_f32 v27, v28, v29
	global_store_dwordx2 v234, v[26:27], s[4:5] sc1
	s_waitcnt vmcnt(7) lgkmcnt(4)
	v_mul_f32_e32 v30, v30, v212
	v_mul_f32_e32 v31, v31, v213
	v_mul_f32_e32 v32, v32, v214
	v_mul_f32_e32 v33, v33, v215
	v_cvt_pk_bf16_f32 v30, v30, v31
	v_cvt_pk_bf16_f32 v31, v32, v33
	global_store_dwordx2 v235, v[30:31], s[4:5] sc1
	s_waitcnt vmcnt(7) lgkmcnt(3)
	v_mul_f32_e32 v2, v2, v216
	v_mul_f32_e32 v3, v3, v217
	v_mul_f32_e32 v4, v4, v218
	v_mul_f32_e32 v5, v5, v219
	v_cvt_pk_bf16_f32 v2, v2, v3
	v_cvt_pk_bf16_f32 v3, v4, v5
	global_store_dwordx2 v236, v[2:3], s[4:5] sc1
	s_waitcnt vmcnt(7) lgkmcnt(2)
	v_mul_f32_e32 v6, v6, v220
	v_mul_f32_e32 v7, v7, v221
	v_mul_f32_e32 v8, v8, v222
	v_mul_f32_e32 v9, v9, v223
	v_cvt_pk_bf16_f32 v6, v6, v7
	v_cvt_pk_bf16_f32 v7, v8, v9
	global_store_dwordx2 v237, v[6:7], s[4:5] sc1
	s_waitcnt vmcnt(7) lgkmcnt(1)
	v_mul_f32_e32 v10, v10, v224
	v_mul_f32_e32 v11, v11, v225
	v_mul_f32_e32 v12, v12, v226
	v_mul_f32_e32 v13, v13, v227
	v_cvt_pk_bf16_f32 v10, v10, v11
	v_cvt_pk_bf16_f32 v11, v12, v13
	global_store_dwordx2 v238, v[10:11], s[4:5] sc1
	s_waitcnt vmcnt(7) lgkmcnt(0)
	v_mul_f32_e32 v14, v14, v228
	v_mul_f32_e32 v15, v15, v229
	v_mul_f32_e32 v16, v16, v230
	v_mul_f32_e32 v17, v17, v231
	v_cvt_pk_bf16_f32 v14, v14, v15
	v_cvt_pk_bf16_f32 v15, v16, v17
	global_store_dwordx2 v239, v[14:15], s[4:5] sc1
	s_waitcnt lgkmcnt(0)
	s_load_dword s10, s[8:9], 0x0
	s_waitcnt lgkmcnt(0)
	s_add_i32 s28, s10, s28
	s_cmpk_lt_i32 s28, 0x200
	s_cbranch_scc1 .LBB0_1133

.Lgm_ph20_loop:
	s_waitcnt lgkmcnt(1)
	v_mfma_f32_32x32x16_bf16 v[82:97], v[240:243], v[252:255], v[82:97]
	ds_read_b128 v[220:223], v210 offset:0
	v_mfma_f32_32x32x16_bf16 v[66:81], v[236:239], v[252:255], v[66:81]
	ds_read_b128 v[232:235], v214 offset:0
	v_mfma_f32_32x32x16_bf16 v[50:65], v[240:243], v[248:251], v[50:65]
	ds_read_b128 v[216:219], v210 offset:4096
	v_mfma_f32_32x32x16_bf16 v[34:49], v[236:239], v[248:251], v[34:49]
	ds_read_b128 v[228:231], v214 offset:4096
	s_waitcnt lgkmcnt(4)
	v_mfma_f32_32x32x16_bf16 v[18:33], v[240:243], v[244:247], v[18:33]
	ds_read_b128 v[224:227], v214 offset:8192
	v_mfma_f32_32x32x16_bf16 v[2:17], v[236:239], v[244:247], v[2:17]
	s_waitcnt lgkmcnt(1)
	v_mfma_f32_32x32x16_bf16 v[82:97], v[220:223], v[232:235], v[82:97]
	ds_read_b128 v[240:243], v209 offset:0
	v_mfma_f32_32x32x16_bf16 v[66:81], v[216:219], v[232:235], v[66:81]
	ds_read_b128 v[252:255], v213 offset:0
	v_mfma_f32_32x32x16_bf16 v[50:65], v[220:223], v[228:231], v[50:65]
	ds_read_b128 v[236:239], v209 offset:4096
	v_mfma_f32_32x32x16_bf16 v[34:49], v[216:219], v[228:231], v[34:49]
	ds_read_b128 v[248:251], v213 offset:4096
	s_waitcnt lgkmcnt(4)
	v_mfma_f32_32x32x16_bf16 v[18:33], v[220:223], v[224:227], v[18:33]
	ds_read_b128 v[244:247], v213 offset:8192
	v_mfma_f32_32x32x16_bf16 v[2:17], v[216:219], v[224:227], v[2:17]
	s_waitcnt lgkmcnt(1)
	v_mfma_f32_32x32x16_bf16 v[82:97], v[240:243], v[252:255], v[82:97]
	ds_read_b128 v[220:223], v208 offset:0
	s_add_u32 s83, s79, s78
	s_add_u32 s83, s83, 2
	s_and_b32 s83, s83, 15
	v_mfma_f32_32x32x16_bf16 v[66:81], v[236:239], v[252:255], v[66:81]
	ds_read_b128 v[232:235], v212 offset:0
	s_lshl_b32 s83, s83, 7
	s_add_u32 s70, s66, s83
	v_mfma_f32_32x32x16_bf16 v[50:65], v[240:243], v[248:251], v[50:65]
	ds_read_b128 v[216:219], v208 offset:4096
	s_addc_u32 s71, s67, 0
	s_add_u32 s72, s68, s83
	v_mfma_f32_32x32x16_bf16 v[34:49], v[236:239], v[248:251], v[34:49]
	ds_read_b128 v[228:231], v212 offset:4096
	s_addc_u32 s73, s69, 0
	s_add_u32 s81, s80, 0x0
	s_add_u32 s82, s80, 0xc000
	s_waitcnt lgkmcnt(4)
	v_mfma_f32_32x32x16_bf16 v[18:33], v[240:243], v[244:247], v[18:33]
	ds_read_b128 v[224:227], v212 offset:8192
	v_mfma_f32_32x32x16_bf16 v[2:17], v[236:239], v[244:247], v[2:17]
	s_waitcnt vmcnt(0) lgkmcnt(0)
	s_barrier
	v_mfma_f32_32x32x16_bf16 v[82:97], v[220:223], v[232:235], v[82:97]
	s_add_u32 m0, s81, 0x0
	ds_read_b128 v[240:243], v211 offset:16384
	global_load_lds_dwordx4 v207, s[70:71]
	s_add_u32 m0, s81, 0x1000
	s_nop 0
	global_load_lds_dwordx4 v206, s[70:71]
	v_mfma_f32_32x32x16_bf16 v[66:81], v[216:219], v[232:235], v[66:81]
	s_add_u32 m0, s81, 0x2000
	ds_read_b128 v[252:255], v215 offset:24576
	global_load_lds_dwordx4 v205, s[70:71]
	s_add_u32 m0, s81, 0x3000
	s_nop 0
	global_load_lds_dwordx4 v204, s[70:71]
	v_mfma_f32_32x32x16_bf16 v[50:65], v[220:223], v[228:231], v[50:65]
	s_add_u32 m0, s81, 0x4000
	ds_read_b128 v[236:239], v211 offset:20480
	global_load_lds_dwordx4 v203, s[70:71]
	s_add_u32 m0, s81, 0x5000
	s_nop 0
	global_load_lds_dwordx4 v202, s[70:71]
	v_mfma_f32_32x32x16_bf16 v[34:49], v[216:219], v[228:231], v[34:49]
	s_add_u32 m0, s82, 0x0
	ds_read_b128 v[248:251], v215 offset:28672
	global_load_lds_dwordx4 v207, s[72:73]
	s_add_u32 m0, s82, 0x1000
	s_nop 0
	global_load_lds_dwordx4 v206, s[72:73]
	v_mfma_f32_32x32x16_bf16 v[18:33], v[220:223], v[224:227], v[18:33]
	s_add_u32 m0, s82, 0x2000
	ds_read_b128 v[244:247], v215 offset:32768
	global_load_lds_dwordx4 v205, s[72:73]
	s_add_u32 m0, s82, 0x3000
	s_nop 0
	global_load_lds_dwordx4 v204, s[72:73]
	v_mfma_f32_32x32x16_bf16 v[2:17], v[216:219], v[224:227], v[2:17]
	s_waitcnt lgkmcnt(1)
	v_mfma_f32_32x32x16_bf16 v[82:97], v[240:243], v[252:255], v[82:97]
	ds_read_b128 v[220:223], v210 offset:16384
	v_mfma_f32_32x32x16_bf16 v[66:81], v[236:239], v[252:255], v[66:81]
	ds_read_b128 v[232:235], v214 offset:24576
	v_mfma_f32_32x32x16_bf16 v[50:65], v[240:243], v[248:251], v[50:65]
	ds_read_b128 v[216:219], v210 offset:20480
	v_mfma_f32_32x32x16_bf16 v[34:49], v[236:239], v[248:251], v[34:49]
	ds_read_b128 v[228:231], v214 offset:28672
	s_waitcnt lgkmcnt(4)
	v_mfma_f32_32x32x16_bf16 v[18:33], v[240:243], v[244:247], v[18:33]
	ds_read_b128 v[224:227], v214 offset:32768
	v_mfma_f32_32x32x16_bf16 v[2:17], v[236:239], v[244:247], v[2:17]
	s_waitcnt lgkmcnt(1)
	v_mfma_f32_32x32x16_bf16 v[82:97], v[220:223], v[232:235], v[82:97]
	ds_read_b128 v[240:243], v209 offset:16384
	v_mfma_f32_32x32x16_bf16 v[66:81], v[216:219], v[232:235], v[66:81]
	ds_read_b128 v[252:255], v213 offset:24576
	v_mfma_f32_32x32x16_bf16 v[50:65], v[220:223], v[228:231], v[50:65]
	ds_read_b128 v[236:239], v209 offset:20480
	v_mfma_f32_32x32x16_bf16 v[34:49], v[216:219], v[228:231], v[34:49]
	ds_read_b128 v[248:251], v213 offset:28672
	s_waitcnt lgkmcnt(4)
	v_mfma_f32_32x32x16_bf16 v[18:33], v[220:223], v[224:227], v[18:33]
	ds_read_b128 v[244:247], v213 offset:32768
	v_mfma_f32_32x32x16_bf16 v[2:17], v[216:219], v[224:227], v[2:17]
	s_waitcnt lgkmcnt(1)
	v_mfma_f32_32x32x16_bf16 v[82:97], v[240:243], v[252:255], v[82:97]
	ds_read_b128 v[220:223], v208 offset:16384
	s_add_u32 s83, s79, s78
	s_add_u32 s83, s83, 3
	s_and_b32 s83, s83, 15
	v_mfma_f32_32x32x16_bf16 v[66:81], v[236:239], v[252:255], v[66:81]
	ds_read_b128 v[232:235], v212 offset:24576
	s_lshl_b32 s83, s83, 7
	s_add_u32 s70, s66, s83
	v_mfma_f32_32x32x16_bf16 v[50:65], v[240:243], v[248:251], v[50:65]
	ds_read_b128 v[216:219], v208 offset:20480
	s_addc_u32 s71, s67, 0
	s_add_u32 s72, s68, s83
	v_mfma_f32_32x32x16_bf16 v[34:49], v[236:239], v[248:251], v[34:49]
	ds_read_b128 v[228:231], v212 offset:28672
	s_addc_u32 s73, s69, 0
	s_add_u32 s81, s80, 0x6000
	s_add_u32 s82, s80, 0x10000
	s_waitcnt lgkmcnt(4)
	v_mfma_f32_32x32x16_bf16 v[18:33], v[240:243], v[244:247], v[18:33]
	ds_read_b128 v[224:227], v212 offset:32768
	v_mfma_f32_32x32x16_bf16 v[2:17], v[236:239], v[244:247], v[2:17]
	s_waitcnt vmcnt(0) lgkmcnt(0)
	s_barrier
	v_mfma_f32_32x32x16_bf16 v[82:97], v[220:223], v[232:235], v[82:97]
	s_add_u32 m0, s81, 0x0
	ds_read_b128 v[240:243], v211 offset:0
	global_load_lds_dwordx4 v207, s[70:71]
	s_add_u32 m0, s81, 0x1000
	s_nop 0
	global_load_lds_dwordx4 v206, s[70:71]
	v_mfma_f32_32x32x16_bf16 v[66:81], v[216:219], v[232:235], v[66:81]
	s_add_u32 m0, s81, 0x2000
	ds_read_b128 v[252:255], v215 offset:0
	global_load_lds_dwordx4 v205, s[70:71]
	s_add_u32 m0, s81, 0x3000
	s_nop 0
	global_load_lds_dwordx4 v204, s[70:71]
	v_mfma_f32_32x32x16_bf16 v[50:65], v[220:223], v[228:231], v[50:65]
	s_add_u32 m0, s81, 0x4000
	ds_read_b128 v[236:239], v211 offset:4096
	global_load_lds_dwordx4 v203, s[70:71]
	s_add_u32 m0, s81, 0x5000
	s_nop 0
	global_load_lds_dwordx4 v202, s[70:71]
	v_mfma_f32_32x32x16_bf16 v[34:49], v[216:219], v[228:231], v[34:49]
	s_add_u32 m0, s82, 0x0
	ds_read_b128 v[248:251], v215 offset:4096
	global_load_lds_dwordx4 v207, s[72:73]
	s_add_u32 m0, s82, 0x1000
	s_nop 0
	global_load_lds_dwordx4 v206, s[72:73]
	v_mfma_f32_32x32x16_bf16 v[18:33], v[220:223], v[224:227], v[18:33]
	s_add_u32 m0, s82, 0x2000
	ds_read_b128 v[244:247], v215 offset:8192
	global_load_lds_dwordx4 v205, s[72:73]
	s_add_u32 m0, s82, 0x3000
	s_nop 0
	global_load_lds_dwordx4 v204, s[72:73]
	v_mfma_f32_32x32x16_bf16 v[2:17], v[216:219], v[224:227], v[2:17]
	s_add_u32 s78, s78, 2
	s_cmp_lt_u32 s78, 14
	s_cbranch_scc1 .Lgm_ph20_loop
	s_waitcnt lgkmcnt(1)
	v_mfma_f32_32x32x16_bf16 v[82:97], v[240:243], v[252:255], v[82:97]
	ds_read_b128 v[220:223], v210 offset:0
	v_mfma_f32_32x32x16_bf16 v[66:81], v[236:239], v[252:255], v[66:81]
	ds_read_b128 v[232:235], v214 offset:0
	v_mfma_f32_32x32x16_bf16 v[50:65], v[240:243], v[248:251], v[50:65]
	ds_read_b128 v[216:219], v210 offset:4096
	v_mfma_f32_32x32x16_bf16 v[34:49], v[236:239], v[248:251], v[34:49]
	ds_read_b128 v[228:231], v214 offset:4096
	s_waitcnt lgkmcnt(4)
	v_mfma_f32_32x32x16_bf16 v[18:33], v[240:243], v[244:247], v[18:33]
	ds_read_b128 v[224:227], v214 offset:8192
	v_mfma_f32_32x32x16_bf16 v[2:17], v[236:239], v[244:247], v[2:17]
	s_waitcnt lgkmcnt(1)
	v_mfma_f32_32x32x16_bf16 v[82:97], v[220:223], v[232:235], v[82:97]
	ds_read_b128 v[240:243], v209 offset:0
	v_mfma_f32_32x32x16_bf16 v[66:81], v[216:219], v[232:235], v[66:81]
	ds_read_b128 v[252:255], v213 offset:0
	v_mfma_f32_32x32x16_bf16 v[50:65], v[220:223], v[228:231], v[50:65]
	ds_read_b128 v[236:239], v209 offset:4096
	v_mfma_f32_32x32x16_bf16 v[34:49], v[216:219], v[228:231], v[34:49]
	ds_read_b128 v[248:251], v213 offset:4096
	s_waitcnt lgkmcnt(4)
	v_mfma_f32_32x32x16_bf16 v[18:33], v[220:223], v[224:227], v[18:33]
	ds_read_b128 v[244:247], v213 offset:8192
	v_mfma_f32_32x32x16_bf16 v[2:17], v[216:219], v[224:227], v[2:17]
	s_waitcnt lgkmcnt(1)
	v_mfma_f32_32x32x16_bf16 v[82:97], v[240:243], v[252:255], v[82:97]
	ds_read_b128 v[220:223], v208 offset:0
	v_mfma_f32_32x32x16_bf16 v[66:81], v[236:239], v[252:255], v[66:81]
	ds_read_b128 v[232:235], v212 offset:0
	v_mfma_f32_32x32x16_bf16 v[50:65], v[240:243], v[248:251], v[50:65]
	ds_read_b128 v[216:219], v208 offset:4096
	v_mfma_f32_32x32x16_bf16 v[34:49], v[236:239], v[248:251], v[34:49]
	ds_read_b128 v[228:231], v212 offset:4096
	s_waitcnt lgkmcnt(4)
	v_mfma_f32_32x32x16_bf16 v[18:33], v[240:243], v[244:247], v[18:33]
	ds_read_b128 v[224:227], v212 offset:8192
	v_mfma_f32_32x32x16_bf16 v[2:17], v[236:239], v[244:247], v[2:17]
	s_waitcnt vmcnt(0) lgkmcnt(0)
	s_barrier
	v_mfma_f32_32x32x16_bf16 v[82:97], v[220:223], v[232:235], v[82:97]
	ds_read_b128 v[240:243], v211 offset:16384
	v_mfma_f32_32x32x16_bf16 v[66:81], v[216:219], v[232:235], v[66:81]
	ds_read_b128 v[252:255], v215 offset:24576
	v_mfma_f32_32x32x16_bf16 v[50:65], v[220:223], v[228:231], v[50:65]
	ds_read_b128 v[236:239], v211 offset:20480
	v_mfma_f32_32x32x16_bf16 v[34:49], v[216:219], v[228:231], v[34:49]
	ds_read_b128 v[248:251], v215 offset:28672
	v_mfma_f32_32x32x16_bf16 v[18:33], v[220:223], v[224:227], v[18:33]
	ds_read_b128 v[244:247], v215 offset:32768
	v_mfma_f32_32x32x16_bf16 v[2:17], v[216:219], v[224:227], v[2:17]
	s_waitcnt lgkmcnt(1)
	v_mfma_f32_32x32x16_bf16 v[82:97], v[240:243], v[252:255], v[82:97]
	ds_read_b128 v[220:223], v210 offset:16384
	v_mfma_f32_32x32x16_bf16 v[66:81], v[236:239], v[252:255], v[66:81]
	ds_read_b128 v[232:235], v214 offset:24576
	v_mfma_f32_32x32x16_bf16 v[50:65], v[240:243], v[248:251], v[50:65]
	ds_read_b128 v[216:219], v210 offset:20480
	v_mfma_f32_32x32x16_bf16 v[34:49], v[236:239], v[248:251], v[34:49]
	ds_read_b128 v[228:231], v214 offset:28672
	s_waitcnt lgkmcnt(4)
	v_mfma_f32_32x32x16_bf16 v[18:33], v[240:243], v[244:247], v[18:33]
	ds_read_b128 v[224:227], v214 offset:32768
	v_mfma_f32_32x32x16_bf16 v[2:17], v[236:239], v[244:247], v[2:17]
	s_waitcnt lgkmcnt(1)
	v_mfma_f32_32x32x16_bf16 v[82:97], v[220:223], v[232:235], v[82:97]
	ds_read_b128 v[240:243], v209 offset:16384
	v_mfma_f32_32x32x16_bf16 v[66:81], v[216:219], v[232:235], v[66:81]
	ds_read_b128 v[252:255], v213 offset:24576
	v_mfma_f32_32x32x16_bf16 v[50:65], v[220:223], v[228:231], v[50:65]
	ds_read_b128 v[236:239], v209 offset:20480
	v_mfma_f32_32x32x16_bf16 v[34:49], v[216:219], v[228:231], v[34:49]
	ds_read_b128 v[248:251], v213 offset:28672
	s_waitcnt lgkmcnt(4)
	v_mfma_f32_32x32x16_bf16 v[18:33], v[220:223], v[224:227], v[18:33]
	ds_read_b128 v[244:247], v213 offset:32768
	v_mfma_f32_32x32x16_bf16 v[2:17], v[216:219], v[224:227], v[2:17]
	s_waitcnt lgkmcnt(1)
	v_mfma_f32_32x32x16_bf16 v[82:97], v[240:243], v[252:255], v[82:97]
	ds_read_b128 v[220:223], v208 offset:16384
	v_mfma_f32_32x32x16_bf16 v[66:81], v[236:239], v[252:255], v[66:81]
	ds_read_b128 v[232:235], v212 offset:24576
	v_mfma_f32_32x32x16_bf16 v[50:65], v[240:243], v[248:251], v[50:65]
	ds_read_b128 v[216:219], v208 offset:20480
	v_mfma_f32_32x32x16_bf16 v[34:49], v[236:239], v[248:251], v[34:49]
	ds_read_b128 v[228:231], v212 offset:28672
	s_waitcnt lgkmcnt(4)
	v_mfma_f32_32x32x16_bf16 v[18:33], v[240:243], v[244:247], v[18:33]
	ds_read_b128 v[224:227], v212 offset:32768
	v_mfma_f32_32x32x16_bf16 v[2:17], v[236:239], v[244:247], v[2:17]
	s_waitcnt vmcnt(0) lgkmcnt(0)
	s_barrier
	v_mfma_f32_32x32x16_bf16 v[82:97], v[220:223], v[232:235], v[82:97]
	v_mfma_f32_32x32x16_bf16 v[66:81], v[216:219], v[232:235], v[66:81]
	v_mfma_f32_32x32x16_bf16 v[50:65], v[220:223], v[228:231], v[50:65]
	v_mfma_f32_32x32x16_bf16 v[34:49], v[216:219], v[228:231], v[34:49]
	v_mfma_f32_32x32x16_bf16 v[18:33], v[220:223], v[224:227], v[18:33]
	v_mfma_f32_32x32x16_bf16 v[2:17], v[216:219], v[224:227], v[2:17]
	s_nop 7
	s_nop 7
	s_waitcnt lgkmcnt(0)
	s_nop 10
	ds_write_b128 v145, v[82:85]
	ds_write_b128 v145, v[86:89] offset:32
	ds_write_b128 v145, v[90:93] offset:64
	ds_write_b128 v145, v[94:97] offset:96
	ds_write_b128 v145, v[66:69] offset:128
	ds_write_b128 v145, v[70:73] offset:160
	ds_write_b128 v145, v[74:77] offset:192
	ds_write_b128 v145, v[78:81] offset:224
	s_waitcnt lgkmcnt(0)
	v_add_u32_e32 v104, s28, v111
	v_or_b32_e32 v244, s29, v119
	v_lshlrev_b32_e32 v242, 2, v244
	v_add_u32_e32 v242, s3, v242
	v_lshlrev_b32_e32 v243, 1, v244
	v_mov_b32_e32 v240, v104
	v_add_u32_e32 v241, 0xfffff000, v240
	v_lshrrev_b32_e32 v241, 11, v241
	v_mad_u32_u24 v241, v241, s26, s26
	v_lshlrev_b32_e32 v241, 2, v241
	v_or_b32_e32 v232, v240, v1
	v_or_b32_e32 v233, v240, v120
	v_or_b32_e32 v234, v240, v121
	v_or_b32_e32 v235, v240, v122
	v_or_b32_e32 v236, v240, v123
	v_or_b32_e32 v237, v240, v124
	v_or_b32_e32 v238, v240, v125
	v_or_b32_e32 v239, v240, v126
	v_cmp_lt_i32_e64 s[82:83], s27, v232
	v_cmp_lt_i32_e64 s[84:85], s27, v233
	v_cmp_lt_i32_e64 s[86:87], s27, v234
	v_cmp_lt_i32_e64 s[88:89], s27, v235
	v_cmp_lt_i32_e64 s[90:91], s27, v236
	v_cmp_lt_i32_e64 s[92:93], s27, v237
	v_cmp_lt_i32_e64 s[94:95], s27, v238
	v_cmp_lt_i32_e64 s[96:97], s27, v239
	s_waitcnt lgkmcnt(0)
	v_cndmask_b32_e64 v200, 0, v241, s[82:83]
	v_cndmask_b32_e64 v204, 0, v241, s[84:85]
	v_cndmask_b32_e64 v208, 0, v241, s[86:87]
	v_cndmask_b32_e64 v212, 0, v241, s[88:89]
	v_cndmask_b32_e64 v216, 0, v241, s[90:91]
	v_cndmask_b32_e64 v220, 0, v241, s[92:93]
	v_cndmask_b32_e64 v224, 0, v241, s[94:95]
	v_cndmask_b32_e64 v228, 0, v241, s[96:97]
	v_add_u32_e32 v200, v200, v242
	v_add_u32_e32 v204, v204, v242
	v_add_u32_e32 v208, v208, v242
	v_add_u32_e32 v212, v212, v242
	v_add_u32_e32 v216, v216, v242
	v_add_u32_e32 v220, v220, v242
	v_add_u32_e32 v224, v224, v242
	v_add_u32_e32 v228, v228, v242
	ds_read_b128 v[82:85], v147
	global_load_dwordx4 v[200:203], v200, s[6:7]
	ds_read_b128 v[86:89], v147 offset:1088
	global_load_dwordx4 v[204:207], v204, s[6:7]
	ds_read_b128 v[90:93], v147 offset:2176
	global_load_dwordx4 v[208:211], v208, s[6:7]
	ds_read_b128 v[94:97], v147 offset:3264
	global_load_dwordx4 v[212:215], v212, s[6:7]
	ds_read_b128 v[66:69], v147 offset:4352
	global_load_dwordx4 v[216:219], v216, s[6:7]
	ds_read_b128 v[70:73], v147 offset:5440
	global_load_dwordx4 v[220:223], v220, s[6:7]
	ds_read_b128 v[74:77], v147 offset:6528
	global_load_dwordx4 v[224:227], v224, s[6:7]
	ds_read_b128 v[78:81], v147 offset:7616
	global_load_dwordx4 v[228:231], v228, s[6:7]
	v_lshl_add_u32 v232, v232, 11, v243
	v_lshl_add_u32 v233, v233, 11, v243
	v_lshl_add_u32 v234, v234, 11, v243
	v_lshl_add_u32 v235, v235, 11, v243
	v_lshl_add_u32 v236, v236, 11, v243
	v_lshl_add_u32 v237, v237, 11, v243
	v_lshl_add_u32 v238, v238, 11, v243
	v_lshl_add_u32 v239, v239, 11, v243
	s_waitcnt vmcnt(7) lgkmcnt(7)
	v_mul_f32_e32 v82, v82, v200
	v_mul_f32_e32 v83, v83, v201
	v_mul_f32_e32 v84, v84, v202
	v_mul_f32_e32 v85, v85, v203
	v_cvt_pk_bf16_f32 v82, v82, v83
	v_cvt_pk_bf16_f32 v83, v84, v85
	global_store_dwordx2 v232, v[82:83], s[4:5] sc1
	s_waitcnt vmcnt(7) lgkmcnt(6)
	v_mul_f32_e32 v86, v86, v204
	v_mul_f32_e32 v87, v87, v205
	v_mul_f32_e32 v88, v88, v206
	v_mul_f32_e32 v89, v89, v207
	v_cvt_pk_bf16_f32 v86, v86, v87
	v_cvt_pk_bf16_f32 v87, v88, v89
	global_store_dwordx2 v233, v[86:87], s[4:5] sc1
	s_waitcnt vmcnt(7) lgkmcnt(5)
	v_mul_f32_e32 v90, v90, v208
	v_mul_f32_e32 v91, v91, v209
	v_mul_f32_e32 v92, v92, v210
	v_mul_f32_e32 v93, v93, v211
	v_cvt_pk_bf16_f32 v90, v90, v91
	v_cvt_pk_bf16_f32 v91, v92, v93
	global_store_dwordx2 v234, v[90:91], s[4:5] sc1
	s_waitcnt vmcnt(7) lgkmcnt(4)
	v_mul_f32_e32 v94, v94, v212
	v_mul_f32_e32 v95, v95, v213
	v_mul_f32_e32 v96, v96, v214
	v_mul_f32_e32 v97, v97, v215
	v_cvt_pk_bf16_f32 v94, v94, v95
	v_cvt_pk_bf16_f32 v95, v96, v97
	global_store_dwordx2 v235, v[94:95], s[4:5] sc1
	s_waitcnt vmcnt(7) lgkmcnt(3)
	v_mul_f32_e32 v66, v66, v216
	v_mul_f32_e32 v67, v67, v217
	v_mul_f32_e32 v68, v68, v218
	v_mul_f32_e32 v69, v69, v219
	v_cvt_pk_bf16_f32 v66, v66, v67
	v_cvt_pk_bf16_f32 v67, v68, v69
	global_store_dwordx2 v236, v[66:67], s[4:5] sc1
	s_waitcnt vmcnt(7) lgkmcnt(2)
	v_mul_f32_e32 v70, v70, v220
	v_mul_f32_e32 v71, v71, v221
	v_mul_f32_e32 v72, v72, v222
	v_mul_f32_e32 v73, v73, v223
	v_cvt_pk_bf16_f32 v70, v70, v71
	v_cvt_pk_bf16_f32 v71, v72, v73
	global_store_dwordx2 v237, v[70:71], s[4:5] sc1
	s_waitcnt vmcnt(7) lgkmcnt(1)
	v_mul_f32_e32 v74, v74, v224
	v_mul_f32_e32 v75, v75, v225
	v_mul_f32_e32 v76, v76, v226
	v_mul_f32_e32 v77, v77, v227
	v_cvt_pk_bf16_f32 v74, v74, v75
	v_cvt_pk_bf16_f32 v75, v76, v77
	global_store_dwordx2 v238, v[74:75], s[4:5] sc1
	s_waitcnt vmcnt(7) lgkmcnt(0)
	v_mul_f32_e32 v78, v78, v228
	v_mul_f32_e32 v79, v79, v229
	v_mul_f32_e32 v80, v80, v230
	v_mul_f32_e32 v81, v81, v231
	v_cvt_pk_bf16_f32 v78, v78, v79
	v_cvt_pk_bf16_f32 v79, v80, v81
	global_store_dwordx2 v239, v[78:79], s[4:5] sc1
	ds_write_b128 v145, v[50:53]
	ds_write_b128 v145, v[54:57] offset:32
	ds_write_b128 v145, v[58:61] offset:64
	ds_write_b128 v145, v[62:65] offset:96
	ds_write_b128 v145, v[34:37] offset:128
	ds_write_b128 v145, v[38:41] offset:160
	ds_write_b128 v145, v[42:45] offset:192
	ds_write_b128 v145, v[46:49] offset:224
	v_add_u32_e32 v240, 0x20, v104
	v_add_u32_e32 v241, 0xfffff000, v240
	v_lshrrev_b32_e32 v241, 11, v241
	v_mad_u32_u24 v241, v241, s26, s26
	v_lshlrev_b32_e32 v241, 2, v241
	v_or_b32_e32 v232, v240, v1
	v_or_b32_e32 v233, v240, v120
	v_or_b32_e32 v234, v240, v121
	v_or_b32_e32 v235, v240, v122
	v_or_b32_e32 v236, v240, v123
	v_or_b32_e32 v237, v240, v124
	v_or_b32_e32 v238, v240, v125
	v_or_b32_e32 v239, v240, v126
	v_cmp_lt_i32_e64 s[82:83], s27, v232
	v_cmp_lt_i32_e64 s[84:85], s27, v233
	v_cmp_lt_i32_e64 s[86:87], s27, v234
	v_cmp_lt_i32_e64 s[88:89], s27, v235
	v_cmp_lt_i32_e64 s[90:91], s27, v236
	v_cmp_lt_i32_e64 s[92:93], s27, v237
	v_cmp_lt_i32_e64 s[94:95], s27, v238
	v_cmp_lt_i32_e64 s[96:97], s27, v239
	s_waitcnt lgkmcnt(0)
	v_cndmask_b32_e64 v200, 0, v241, s[82:83]
	v_cndmask_b32_e64 v204, 0, v241, s[84:85]
	v_cndmask_b32_e64 v208, 0, v241, s[86:87]
	v_cndmask_b32_e64 v212, 0, v241, s[88:89]
	v_cndmask_b32_e64 v216, 0, v241, s[90:91]
	v_cndmask_b32_e64 v220, 0, v241, s[92:93]
	v_cndmask_b32_e64 v224, 0, v241, s[94:95]
	v_cndmask_b32_e64 v228, 0, v241, s[96:97]
	v_add_u32_e32 v200, v200, v242
	v_add_u32_e32 v204, v204, v242
	v_add_u32_e32 v208, v208, v242
	v_add_u32_e32 v212, v212, v242
	v_add_u32_e32 v216, v216, v242
	v_add_u32_e32 v220, v220, v242
	v_add_u32_e32 v224, v224, v242
	v_add_u32_e32 v228, v228, v242
	ds_read_b128 v[50:53], v147
	global_load_dwordx4 v[200:203], v200, s[6:7]
	ds_read_b128 v[54:57], v147 offset:1088
	global_load_dwordx4 v[204:207], v204, s[6:7]
	ds_read_b128 v[58:61], v147 offset:2176
	global_load_dwordx4 v[208:211], v208, s[6:7]
	ds_read_b128 v[62:65], v147 offset:3264
	global_load_dwordx4 v[212:215], v212, s[6:7]
	ds_read_b128 v[34:37], v147 offset:4352
	global_load_dwordx4 v[216:219], v216, s[6:7]
	ds_read_b128 v[38:41], v147 offset:5440
	global_load_dwordx4 v[220:223], v220, s[6:7]
	ds_read_b128 v[42:45], v147 offset:6528
	global_load_dwordx4 v[224:227], v224, s[6:7]
	ds_read_b128 v[46:49], v147 offset:7616
	global_load_dwordx4 v[228:231], v228, s[6:7]
	v_lshl_add_u32 v232, v232, 11, v243
	v_lshl_add_u32 v233, v233, 11, v243
	v_lshl_add_u32 v234, v234, 11, v243
	v_lshl_add_u32 v235, v235, 11, v243
	v_lshl_add_u32 v236, v236, 11, v243
	v_lshl_add_u32 v237, v237, 11, v243
	v_lshl_add_u32 v238, v238, 11, v243
	v_lshl_add_u32 v239, v239, 11, v243
	s_waitcnt vmcnt(7) lgkmcnt(7)
	v_mul_f32_e32 v50, v50, v200
	v_mul_f32_e32 v51, v51, v201
	v_mul_f32_e32 v52, v52, v202
	v_mul_f32_e32 v53, v53, v203
	v_cvt_pk_bf16_f32 v50, v50, v51
	v_cvt_pk_bf16_f32 v51, v52, v53
	global_store_dwordx2 v232, v[50:51], s[4:5] sc1
	s_waitcnt vmcnt(7) lgkmcnt(6)
	v_mul_f32_e32 v54, v54, v204
	v_mul_f32_e32 v55, v55, v205
	v_mul_f32_e32 v56, v56, v206
	v_mul_f32_e32 v57, v57, v207
	v_cvt_pk_bf16_f32 v54, v54, v55
	v_cvt_pk_bf16_f32 v55, v56, v57
	global_store_dwordx2 v233, v[54:55], s[4:5] sc1
	s_waitcnt vmcnt(7) lgkmcnt(5)
	v_mul_f32_e32 v58, v58, v208
	v_mul_f32_e32 v59, v59, v209
	v_mul_f32_e32 v60, v60, v210
	v_mul_f32_e32 v61, v61, v211
	v_cvt_pk_bf16_f32 v58, v58, v59
	v_cvt_pk_bf16_f32 v59, v60, v61
	global_store_dwordx2 v234, v[58:59], s[4:5] sc1
	s_waitcnt vmcnt(7) lgkmcnt(4)
	v_mul_f32_e32 v62, v62, v212
	v_mul_f32_e32 v63, v63, v213
	v_mul_f32_e32 v64, v64, v214
	v_mul_f32_e32 v65, v65, v215
	v_cvt_pk_bf16_f32 v62, v62, v63
	v_cvt_pk_bf16_f32 v63, v64, v65
	global_store_dwordx2 v235, v[62:63], s[4:5] sc1
	s_waitcnt vmcnt(7) lgkmcnt(3)
	v_mul_f32_e32 v34, v34, v216
	v_mul_f32_e32 v35, v35, v217
	v_mul_f32_e32 v36, v36, v218
	v_mul_f32_e32 v37, v37, v219
	v_cvt_pk_bf16_f32 v34, v34, v35
	v_cvt_pk_bf16_f32 v35, v36, v37
	global_store_dwordx2 v236, v[34:35], s[4:5] sc1
	s_waitcnt vmcnt(7) lgkmcnt(2)
	v_mul_f32_e32 v38, v38, v220
	v_mul_f32_e32 v39, v39, v221
	v_mul_f32_e32 v40, v40, v222
	v_mul_f32_e32 v41, v41, v223
	v_cvt_pk_bf16_f32 v38, v38, v39
	v_cvt_pk_bf16_f32 v39, v40, v41
	global_store_dwordx2 v237, v[38:39], s[4:5] sc1
	s_waitcnt vmcnt(7) lgkmcnt(1)
	v_mul_f32_e32 v42, v42, v224
	v_mul_f32_e32 v43, v43, v225
	v_mul_f32_e32 v44, v44, v226
	v_mul_f32_e32 v45, v45, v227
	v_cvt_pk_bf16_f32 v42, v42, v43
	v_cvt_pk_bf16_f32 v43, v44, v45
	global_store_dwordx2 v238, v[42:43], s[4:5] sc1
	s_waitcnt vmcnt(7) lgkmcnt(0)
	v_mul_f32_e32 v46, v46, v228
	v_mul_f32_e32 v47, v47, v229
	v_mul_f32_e32 v48, v48, v230
	v_mul_f32_e32 v49, v49, v231
	v_cvt_pk_bf16_f32 v46, v46, v47
	v_cvt_pk_bf16_f32 v47, v48, v49
	global_store_dwordx2 v239, v[46:47], s[4:5] sc1
	ds_write_b128 v145, v[18:21]
	ds_write_b128 v145, v[22:25] offset:32
	ds_write_b128 v145, v[26:29] offset:64
	ds_write_b128 v145, v[30:33] offset:96
	ds_write_b128 v145, v[2:5] offset:128
	ds_write_b128 v145, v[6:9] offset:160
	ds_write_b128 v145, v[10:13] offset:192
	ds_write_b128 v145, v[14:17] offset:224
	v_add_u32_e32 v240, 0x40, v104
	v_add_u32_e32 v241, 0xfffff000, v240
	v_lshrrev_b32_e32 v241, 11, v241
	v_mad_u32_u24 v241, v241, s26, s26
	v_lshlrev_b32_e32 v241, 2, v241
	v_or_b32_e32 v232, v240, v1
	v_or_b32_e32 v233, v240, v120
	v_or_b32_e32 v234, v240, v121
	v_or_b32_e32 v235, v240, v122
	v_or_b32_e32 v236, v240, v123
	v_or_b32_e32 v237, v240, v124
	v_or_b32_e32 v238, v240, v125
	v_or_b32_e32 v239, v240, v126
	v_cmp_lt_i32_e64 s[82:83], s27, v232
	v_cmp_lt_i32_e64 s[84:85], s27, v233
	v_cmp_lt_i32_e64 s[86:87], s27, v234
	v_cmp_lt_i32_e64 s[88:89], s27, v235
	v_cmp_lt_i32_e64 s[90:91], s27, v236
	v_cmp_lt_i32_e64 s[92:93], s27, v237
	v_cmp_lt_i32_e64 s[94:95], s27, v238
	v_cmp_lt_i32_e64 s[96:97], s27, v239
	s_waitcnt lgkmcnt(0)
	v_cndmask_b32_e64 v200, 0, v241, s[82:83]
	v_cndmask_b32_e64 v204, 0, v241, s[84:85]
	v_cndmask_b32_e64 v208, 0, v241, s[86:87]
	v_cndmask_b32_e64 v212, 0, v241, s[88:89]
	v_cndmask_b32_e64 v216, 0, v241, s[90:91]
	v_cndmask_b32_e64 v220, 0, v241, s[92:93]
	v_cndmask_b32_e64 v224, 0, v241, s[94:95]
	v_cndmask_b32_e64 v228, 0, v241, s[96:97]
	v_add_u32_e32 v200, v200, v242
	v_add_u32_e32 v204, v204, v242
	v_add_u32_e32 v208, v208, v242
	v_add_u32_e32 v212, v212, v242
	v_add_u32_e32 v216, v216, v242
	v_add_u32_e32 v220, v220, v242
	v_add_u32_e32 v224, v224, v242
	v_add_u32_e32 v228, v228, v242
	ds_read_b128 v[18:21], v147
	global_load_dwordx4 v[200:203], v200, s[6:7]
	ds_read_b128 v[22:25], v147 offset:1088
	global_load_dwordx4 v[204:207], v204, s[6:7]
	ds_read_b128 v[26:29], v147 offset:2176
	global_load_dwordx4 v[208:211], v208, s[6:7]
	ds_read_b128 v[30:33], v147 offset:3264
	global_load_dwordx4 v[212:215], v212, s[6:7]
	ds_read_b128 v[2:5], v147 offset:4352
	global_load_dwordx4 v[216:219], v216, s[6:7]
	ds_read_b128 v[6:9], v147 offset:5440
	global_load_dwordx4 v[220:223], v220, s[6:7]
	ds_read_b128 v[10:13], v147 offset:6528
	global_load_dwordx4 v[224:227], v224, s[6:7]
	ds_read_b128 v[14:17], v147 offset:7616
	global_load_dwordx4 v[228:231], v228, s[6:7]
	v_lshl_add_u32 v232, v232, 11, v243
	v_lshl_add_u32 v233, v233, 11, v243
	v_lshl_add_u32 v234, v234, 11, v243
	v_lshl_add_u32 v235, v235, 11, v243
	v_lshl_add_u32 v236, v236, 11, v243
	v_lshl_add_u32 v237, v237, 11, v243
	v_lshl_add_u32 v238, v238, 11, v243
	v_lshl_add_u32 v239, v239, 11, v243
	s_waitcnt vmcnt(7) lgkmcnt(7)
	v_mul_f32_e32 v18, v18, v200
	v_mul_f32_e32 v19, v19, v201
	v_mul_f32_e32 v20, v20, v202
	v_mul_f32_e32 v21, v21, v203
	v_cvt_pk_bf16_f32 v18, v18, v19
	v_cvt_pk_bf16_f32 v19, v20, v21
	global_store_dwordx2 v232, v[18:19], s[4:5] sc1
	s_waitcnt vmcnt(7) lgkmcnt(6)
	v_mul_f32_e32 v22, v22, v204
	v_mul_f32_e32 v23, v23, v205
	v_mul_f32_e32 v24, v24, v206
	v_mul_f32_e32 v25, v25, v207
	v_cvt_pk_bf16_f32 v22, v22, v23
	v_cvt_pk_bf16_f32 v23, v24, v25
	global_store_dwordx2 v233, v[22:23], s[4:5] sc1
	s_waitcnt vmcnt(7) lgkmcnt(5)
	v_mul_f32_e32 v26, v26, v208
	v_mul_f32_e32 v27, v27, v209
	v_mul_f32_e32 v28, v28, v210
	v_mul_f32_e32 v29, v29, v211
	v_cvt_pk_bf16_f32 v26, v26, v27
	v_cvt_pk_bf16_f32 v27, v28, v29
	global_store_dwordx2 v234, v[26:27], s[4:5] sc1
	s_waitcnt vmcnt(7) lgkmcnt(4)
	v_mul_f32_e32 v30, v30, v212
	v_mul_f32_e32 v31, v31, v213
	v_mul_f32_e32 v32, v32, v214
	v_mul_f32_e32 v33, v33, v215
	v_cvt_pk_bf16_f32 v30, v30, v31
	v_cvt_pk_bf16_f32 v31, v32, v33
	global_store_dwordx2 v235, v[30:31], s[4:5] sc1
	s_waitcnt vmcnt(7) lgkmcnt(3)
	v_mul_f32_e32 v2, v2, v216
	v_mul_f32_e32 v3, v3, v217
	v_mul_f32_e32 v4, v4, v218
	v_mul_f32_e32 v5, v5, v219
	v_cvt_pk_bf16_f32 v2, v2, v3
	v_cvt_pk_bf16_f32 v3, v4, v5
	global_store_dwordx2 v236, v[2:3], s[4:5] sc1
	s_waitcnt vmcnt(7) lgkmcnt(2)
	v_mul_f32_e32 v6, v6, v220
	v_mul_f32_e32 v7, v7, v221
	v_mul_f32_e32 v8, v8, v222
	v_mul_f32_e32 v9, v9, v223
	v_cvt_pk_bf16_f32 v6, v6, v7
	v_cvt_pk_bf16_f32 v7, v8, v9
	global_store_dwordx2 v237, v[6:7], s[4:5] sc1
	s_waitcnt vmcnt(7) lgkmcnt(1)
	v_mul_f32_e32 v10, v10, v224
	v_mul_f32_e32 v11, v11, v225
	v_mul_f32_e32 v12, v12, v226
	v_mul_f32_e32 v13, v13, v227
	v_cvt_pk_bf16_f32 v10, v10, v11
	v_cvt_pk_bf16_f32 v11, v12, v13
	global_store_dwordx2 v238, v[10:11], s[4:5] sc1
	s_waitcnt vmcnt(7) lgkmcnt(0)
	v_mul_f32_e32 v14, v14, v228
	v_mul_f32_e32 v15, v15, v229
	v_mul_f32_e32 v16, v16, v230
	v_mul_f32_e32 v17, v17, v231
	v_cvt_pk_bf16_f32 v14, v14, v15
	v_cvt_pk_bf16_f32 v15, v16, v17
	global_store_dwordx2 v239, v[14:15], s[4:5] sc1
	s_waitcnt lgkmcnt(0)
	s_load_dword s10, s[8:9], 0x0
	s_waitcnt lgkmcnt(0)
	s_add_i32 s2, s10, s2
	s_cmpk_lt_i32 s2, 0x200
	s_cbranch_scc1 .LBB0_2331

.LBB0_2365:
	s_andn2_saveexec_b64 s[6:7], s[6:7]
	s_cbranch_execz .LBB0_2383
	s_mov_b64 s[8:9], exec
	buffer_wbl2 sc1
	buffer_inv sc1
	s_waitcnt vmcnt(0)
	v_mbcnt_lo_u32_b32 v3, s8, 0
	v_mbcnt_hi_u32_b32 v3, s9, v3
	v_cmp_eq_u32_e32 vcc, 0, v3
	s_and_saveexec_b64 s[10:11], vcc
	s_cbranch_execz .LBB0_2368
	s_bcnt1_i32_b64 s8, s[8:9]
	v_mov_b32_e32 v5, 0x3000
	v_mov_b32_e32 v6, s8
	global_atomic_add v5, v5, v6, s[20:21] offset:1024 sc0

.LBB0_2382:
	s_or_b64 exec, exec, s[8:9]
	v_mov_b32_e32 v3, 0x2000
	v_mov_b32_e32 v5, 1
	s_waitcnt vmcnt(0)
	global_atomic_add v3, v5, s[4:5] offset:1024
	s_waitcnt vmcnt(0)

.LBB0_2430:
	s_andn2_saveexec_b64 s[8:9], s[8:9]
	s_cbranch_execz .LBB0_2448
	s_mov_b64 s[8:9], exec
	buffer_wbl2 sc1
	buffer_inv sc1
	s_waitcnt vmcnt(0)
	v_mbcnt_lo_u32_b32 v1, s8, 0
	v_mbcnt_hi_u32_b32 v1, s9, v1
	v_cmp_eq_u32_e32 vcc, 0, v1
	s_and_saveexec_b64 s[10:11], vcc
	s_cbranch_execz .LBB0_2433
	s_bcnt1_i32_b64 s8, s[8:9]
	v_mov_b32_e32 v2, 0x3000
	v_mov_b32_e32 v3, s8
	global_atomic_add v2, v2, v3, s[20:21] offset:1024 sc0

.LBB0_2447:
	s_or_b64 exec, exec, s[8:9]
	v_mov_b32_e32 v1, 0x2000
	v_mov_b32_e32 v2, 1
	s_waitcnt vmcnt(0)
	global_atomic_add v1, v2, s[4:5] offset:1024
	s_waitcnt vmcnt(0)
